# GEMM MFMA phases: all s_setprio toggles and the duplicate post-barrier lgkmcnt wait removed
# baseline (speedup 1.0000x reference)
; #define PG8_STAGE(bufoff, gbase, voff) do { _Pragma("unroll") for (int _i = 0; _i < 2; ++_i) \
;         __builtin_amdgcn_global_load_lds((const unsigned*)((const char*)(gbase) + (voff)[_i]), (PG8_LAS unsigned*)(lds + (bufoff) + ldsw + _i * 8192), 16, 0, 0); } while (0)
; #define PG8_LDA(dst, b, h) do { _Pragma("unroll") for (int m = 0; m < 4; ++m) _Pragma("unroll") for (int k = 0; k < 2; ++k) dst[m][k] = *(const PG8_LAS bf16x8*)(lds + PG8_SA(b, h) + aoff + m * 2048 + k * 1024); } while (0)
; #define PG8_LDB(dst, b, h) do { _Pragma("unroll") for (int n = 0; n < 2; ++n) _Pragma("unroll") for (int k = 0; k < 2; ++k) dst[n][k] = *(const PG8_LAS bf16x8*)(lds + PG8_SB(b, h) + boff + n * 2048 + k * 1024); } while (0)
; #define PG8_MMA(ai, bj, At, Bt) do { __builtin_amdgcn_s_setprio(1); _Pragma("unroll") for (int m = 0; m < 4; ++m) _Pragma("unroll") for (int n = 0; n < 2; ++n) _Pragma("unroll") for (int k = 0; k < 2; ++k) \
;         acc[ai][bj][m][n] = __builtin_amdgcn_mfma_f32_16x16x32_bf16(Bt[n][k], At[m][k], acc[ai][bj][m][n], 0, 0, 0); __builtin_amdgcn_s_setprio(0); } while (0)
; #define PG8_WAIT_V(n) asm volatile("s_waitcnt vmcnt(" #n ")" ::: "memory")
; #define PG8_WAIT_L(n) asm volatile("s_waitcnt lgkmcnt(" #n ")" ::: "memory")
; template <class Epi, class Sched, bool ALIGN_EPI = false, bool SP2 = false>
; __device__ __forceinline__ void gemm_phase(PG8_LAS unsigned char* lds, const Gemm g, const Sched& S, const Epi& E) {
;     ...
;             const bool last = (t == nt - 2);
;             const char* a1 = cA + (size_t)(t + 1) * kstep;
;             const char* a2 = last ? nA : cA + (size_t)(t + 2) * kstep; const char* b2 = last ? nB : cB + (size_t)(t + 2) * kstep;
;             const char* a3 = a2 + kstep; const char* b3 = b2 + kstep;
;             if (last && has_next) S.a_ready(nxt);
;             if constexpr (SP2) {
;             PG8_LDB(B0, 0, 0); PG8_LDB(B1, 0, 1); PG8_SCHED; PG8_LDA(At, 0, 0); PG8_STAGE(PG8_SA(1, 1), a1 + hstep, voffA);
;             PG8_WAIT_V(8); PG8_WAIT_L(0); PG8_BAR; PG8_MMA(0, 0, At, B0); PG8_MMA(0, 1, At, B1); PG8_BAR; PG8_SCHED;
;             PG8_LDA(At, 0, 1); PG8_STAGE(PG8_SB(0, 0), b2, voffB); PG8_STAGE(PG8_SB(0, 1), b2 + hstep, voffB); PG8_STAGE(PG8_SA(0, 0), a2, voffA);
;             PG8_WAIT_V(8); PG8_WAIT_L(0); PG8_BAR; PG8_MMA(1, 0, At, B0); PG8_MMA(1, 1, At, B1); PG8_BAR; PG8_SCHED;
.LBB0_165:
	s_add_u32 s28, s26, 0xfff80080
	s_addc_u32 s29, s27, -1
	s_add_i32 s78, 0, 0x10000
	s_cmp_eq_u32 s77, 28
	s_cselect_b32 s41, s17, s29
	s_cselect_b32 s40, s25, s28
	s_cselect_b32 s29, s23, s73
	s_cselect_b32 s28, s54, s55
	s_add_i32 s80, 0, 0x14000
	v_add_u32_e32 v154, s78, v161
	v_add_u32_e32 v158, s80, v161
	ds_read_b128 v[130:133], v154
	ds_read_b128 v[146:149], v154 offset:1024
	ds_read_b128 v[150:153], v154 offset:2048
	ds_read_b128 v[154:157], v154 offset:3072
	ds_read_b128 v[180:183], v158
	ds_read_b128 v[184:187], v158 offset:1024
	ds_read_b128 v[188:191], v158 offset:2048
	ds_read_b128 v[192:195], v158 offset:3072
	v_lshl_add_u64 v[158:159], s[26:27], 0, v[142:143]
	s_add_i32 m0, s45, 0xc000
	ds_read_b128 v[196:199], v164
	ds_read_b128 v[200:203], v164 offset:1024
	ds_read_b128 v[218:221], v164 offset:2048
	ds_read_b128 v[222:225], v164 offset:3072
	ds_read_b128 v[226:229], v164 offset:4096
	ds_read_b128 v[230:233], v164 offset:5120
	ds_read_b128 v[234:237], v164 offset:6144
	ds_read_b128 v[238:241], v164 offset:7168
	global_load_lds_dwordx4 v[158:159], off
	v_lshl_add_u64 v[158:159], s[26:27], 0, v[144:145]
	s_add_i32 m0, s45, 0xe000
	s_nop 0
	global_load_lds_dwordx4 v[158:159], off
	s_waitcnt vmcnt(8)
	s_waitcnt lgkmcnt(0)
	s_barrier
	v_mfma_f32_16x16x32_bf16 v[126:129], v[130:133], v[196:199], v[126:129]
	v_mfma_f32_16x16x32_bf16 v[118:121], v[150:153], v[196:199], v[118:121]
	v_mfma_f32_16x16x32_bf16 v[110:113], v[130:133], v[218:221], v[110:113]
	v_mfma_f32_16x16x32_bf16 v[102:105], v[150:153], v[218:221], v[102:105]
	v_mfma_f32_16x16x32_bf16 v[94:97], v[130:133], v[226:229], v[94:97]
	v_mfma_f32_16x16x32_bf16 v[86:89], v[150:153], v[226:229], v[86:89]
	v_mfma_f32_16x16x32_bf16 v[78:81], v[130:133], v[234:237], v[78:81]
	v_mfma_f32_16x16x32_bf16 v[70:73], v[150:153], v[234:237], v[70:73]
	v_mfma_f32_16x16x32_bf16 v[126:129], v[146:149], v[200:203], v[126:129]
	v_mfma_f32_16x16x32_bf16 v[118:121], v[154:157], v[200:203], v[118:121]
	v_mfma_f32_16x16x32_bf16 v[110:113], v[146:149], v[222:225], v[110:113]
	v_mfma_f32_16x16x32_bf16 v[102:105], v[154:157], v[222:225], v[102:105]
	v_mfma_f32_16x16x32_bf16 v[94:97], v[146:149], v[230:233], v[94:97]
	v_mfma_f32_16x16x32_bf16 v[86:89], v[154:157], v[230:233], v[86:89]
	v_mfma_f32_16x16x32_bf16 v[78:81], v[146:149], v[238:241], v[78:81]
	v_mfma_f32_16x16x32_bf16 v[70:73], v[154:157], v[238:241], v[70:73]
	v_mfma_f32_16x16x32_bf16 v[122:125], v[180:183], v[196:199], v[122:125]
	v_mfma_f32_16x16x32_bf16 v[114:117], v[188:191], v[196:199], v[114:117]
	v_mfma_f32_16x16x32_bf16 v[106:109], v[180:183], v[218:221], v[106:109]
	v_mfma_f32_16x16x32_bf16 v[98:101], v[188:191], v[218:221], v[98:101]
	v_mfma_f32_16x16x32_bf16 v[90:93], v[180:183], v[226:229], v[90:93]
	v_mfma_f32_16x16x32_bf16 v[82:85], v[188:191], v[226:229], v[82:85]
	v_mfma_f32_16x16x32_bf16 v[74:77], v[180:183], v[234:237], v[74:77]
	v_mfma_f32_16x16x32_bf16 v[66:69], v[188:191], v[234:237], v[66:69]
	v_mfma_f32_16x16x32_bf16 v[122:125], v[184:187], v[200:203], v[122:125]
	v_mfma_f32_16x16x32_bf16 v[114:117], v[192:195], v[200:203], v[114:117]
	v_mfma_f32_16x16x32_bf16 v[106:109], v[184:187], v[222:225], v[106:109]
	v_mfma_f32_16x16x32_bf16 v[98:101], v[192:195], v[222:225], v[98:101]
	v_mfma_f32_16x16x32_bf16 v[90:93], v[184:187], v[230:233], v[90:93]
	v_mfma_f32_16x16x32_bf16 v[82:85], v[192:195], v[230:233], v[82:85]
	v_mfma_f32_16x16x32_bf16 v[74:77], v[184:187], v[238:241], v[74:77]
	v_mfma_f32_16x16x32_bf16 v[66:69], v[192:195], v[238:241], v[66:69]
	s_barrier
	s_add_i32 s78, s78, s46
	v_lshl_add_u64 v[158:159], s[28:29], 0, v[0:1]
	s_mov_b32 m0, s78
	ds_read_b128 v[196:199], v164 offset:16384
	ds_read_b128 v[200:203], v164 offset:17408
	ds_read_b128 v[218:221], v164 offset:18432
	ds_read_b128 v[222:225], v164 offset:19456
	ds_read_b128 v[226:229], v164 offset:20480
	ds_read_b128 v[230:233], v164 offset:21504
	ds_read_b128 v[234:237], v164 offset:22528
	ds_read_b128 v[238:241], v164 offset:23552
	global_load_lds_dwordx4 v[158:159], off
	s_add_i32 m0, s78, 0x2000
	s_add_u32 vcc_lo, s28, 0x80000
	v_lshl_add_u64 v[166:167], s[28:29], 0, v[134:135]
	s_addc_u32 vcc_hi, s29, 0
	s_add_i32 s78, s80, s46
	global_load_lds_dwordx4 v[166:167], off
	v_lshl_add_u64 v[242:243], vcc, 0, v[0:1]
	s_mov_b32 m0, s78
	v_lshl_add_u64 v[244:245], s[40:41], 0, v[136:137]
	global_load_lds_dwordx4 v[242:243], off
	v_lshl_add_u64 v[242:243], vcc, 0, v[134:135]
	s_add_i32 m0, s78, 0x2000
	s_nop 0
	global_load_lds_dwordx4 v[242:243], off
	v_lshl_add_u64 v[242:243], s[40:41], 0, v[138:139]
	s_mov_b32 m0, s45
	s_nop 0
	global_load_lds_dwordx4 v[242:243], off
	s_mov_b32 m0, s49
	s_nop 0
	global_load_lds_dwordx4 v[244:245], off
	s_waitcnt vmcnt(8)
	s_waitcnt lgkmcnt(0)
	s_barrier
; #define PG8_STAGE(bufoff, gbase, voff) do { _Pragma("unroll") for (int _i = 0; _i < 2; ++_i) \
;         __builtin_amdgcn_global_load_lds((const unsigned*)((const char*)(gbase) + (voff)[_i]), (PG8_LAS unsigned*)(lds + (bufoff) + ldsw + _i * 8192), 16, 0, 0); } while (0)
; #define PG8_LDA(dst, b, h) do { _Pragma("unroll") for (int m = 0; m < 4; ++m) _Pragma("unroll") for (int k = 0; k < 2; ++k) dst[m][k] = *(const PG8_LAS bf16x8*)(lds + PG8_SA(b, h) + aoff + m * 2048 + k * 1024); } while (0)
; #define PG8_LDB(dst, b, h) do { _Pragma("unroll") for (int n = 0; n < 2; ++n) _Pragma("unroll") for (int k = 0; k < 2; ++k) dst[n][k] = *(const PG8_LAS bf16x8*)(lds + PG8_SB(b, h) + boff + n * 2048 + k * 1024); } while (0)
; #define PG8_MMA(ai, bj, At, Bt) do { __builtin_amdgcn_s_setprio(1); _Pragma("unroll") for (int m = 0; m < 4; ++m) _Pragma("unroll") for (int n = 0; n < 2; ++n) _Pragma("unroll") for (int k = 0; k < 2; ++k) \
;         acc[ai][bj][m][n] = __builtin_amdgcn_mfma_f32_16x16x32_bf16(Bt[n][k], At[m][k], acc[ai][bj][m][n], 0, 0, 0); __builtin_amdgcn_s_setprio(0); } while (0)
; #define PG8_WAIT_V(n) asm volatile("s_waitcnt vmcnt(" #n ")" ::: "memory")
; #define PG8_WAIT_L(n) asm volatile("s_waitcnt lgkmcnt(" #n ")" ::: "memory")
; #define PG8_BAR __builtin_amdgcn_s_barrier()
; #define PG8_SCHED __builtin_amdgcn_sched_barrier(0)
; template <class Epi, class Sched, bool ALIGN_EPI = false, bool SP2 = false>
; __device__ __forceinline__ void gemm_phase(PG8_LAS unsigned char* lds, const Gemm g, const Sched& S, const Epi& E) {
;     ...
;             PG8_WAIT_V(8); PG8_WAIT_L(0); PG8_BAR; PG8_MMA(1, 0, At, B0); PG8_MMA(1, 1, At, B1); PG8_BAR; PG8_SCHED;
;             PG8_LDB(B0, 1, 0); PG8_LDB(B1, 1, 1); PG8_SCHED; PG8_LDA(At, 1, 0); PG8_STAGE(PG8_SA(0, 1), a2 + hstep, voffA);
;             PG8_WAIT_V(8); PG8_WAIT_L(0); PG8_BAR; PG8_MMA(0, 0, At, B0); PG8_MMA(0, 1, At, B1); PG8_BAR; PG8_SCHED;
	v_mfma_f32_16x16x32_bf16 v[62:65], v[130:133], v[196:199], v[62:65]
	v_mfma_f32_16x16x32_bf16 v[54:57], v[150:153], v[196:199], v[54:57]
	v_mfma_f32_16x16x32_bf16 v[46:49], v[130:133], v[218:221], v[46:49]
	v_mfma_f32_16x16x32_bf16 v[38:41], v[150:153], v[218:221], v[38:41]
	v_mfma_f32_16x16x32_bf16 v[30:33], v[130:133], v[226:229], v[30:33]
	v_mfma_f32_16x16x32_bf16 v[22:25], v[150:153], v[226:229], v[22:25]
	v_mfma_f32_16x16x32_bf16 v[14:17], v[130:133], v[234:237], v[14:17]
	v_mfma_f32_16x16x32_bf16 v[6:9], v[150:153], v[234:237], v[6:9]
	v_mfma_f32_16x16x32_bf16 v[62:65], v[146:149], v[200:203], v[62:65]
	v_mfma_f32_16x16x32_bf16 v[54:57], v[154:157], v[200:203], v[54:57]
	v_mfma_f32_16x16x32_bf16 v[46:49], v[146:149], v[222:225], v[46:49]
	v_mfma_f32_16x16x32_bf16 v[38:41], v[154:157], v[222:225], v[38:41]
	v_mfma_f32_16x16x32_bf16 v[30:33], v[146:149], v[230:233], v[30:33]
	v_mfma_f32_16x16x32_bf16 v[22:25], v[154:157], v[230:233], v[22:25]
	v_mfma_f32_16x16x32_bf16 v[14:17], v[146:149], v[238:241], v[14:17]
	v_mfma_f32_16x16x32_bf16 v[6:9], v[154:157], v[238:241], v[6:9]
	v_mfma_f32_16x16x32_bf16 v[58:61], v[180:183], v[196:199], v[58:61]
	v_mfma_f32_16x16x32_bf16 v[50:53], v[188:191], v[196:199], v[50:53]
	v_mfma_f32_16x16x32_bf16 v[42:45], v[180:183], v[218:221], v[42:45]
	v_mfma_f32_16x16x32_bf16 v[34:37], v[188:191], v[218:221], v[34:37]
	v_mfma_f32_16x16x32_bf16 v[26:29], v[180:183], v[226:229], v[26:29]
	v_mfma_f32_16x16x32_bf16 v[18:21], v[188:191], v[226:229], v[18:21]
	v_mfma_f32_16x16x32_bf16 v[10:13], v[180:183], v[234:237], v[10:13]
	v_mfma_f32_16x16x32_bf16 v[2:5], v[188:191], v[234:237], v[2:5]
	v_mfma_f32_16x16x32_bf16 v[58:61], v[184:187], v[200:203], v[58:61]
	v_mfma_f32_16x16x32_bf16 v[50:53], v[192:195], v[200:203], v[50:53]
	v_mfma_f32_16x16x32_bf16 v[42:45], v[184:187], v[222:225], v[42:45]
	v_mfma_f32_16x16x32_bf16 v[34:37], v[192:195], v[222:225], v[34:37]
	v_mfma_f32_16x16x32_bf16 v[26:29], v[184:187], v[230:233], v[26:29]
	v_mfma_f32_16x16x32_bf16 v[18:21], v[192:195], v[230:233], v[18:21]
	v_mfma_f32_16x16x32_bf16 v[10:13], v[184:187], v[238:241], v[10:13]
	v_mfma_f32_16x16x32_bf16 v[2:5], v[192:195], v[238:241], v[2:5]
	s_barrier
	s_add_i32 s78, 0, 0x18000
	s_add_i32 s80, 0, 0x1c000
	v_add_u32_e32 v154, s78, v161
	v_add_u32_e32 v165, s80, v161
	ds_read_b128 v[130:133], v154
	ds_read_b128 v[146:149], v154 offset:1024
	ds_read_b128 v[150:153], v154 offset:2048
	ds_read_b128 v[154:157], v154 offset:3072
	ds_read_b128 v[180:183], v165
	ds_read_b128 v[184:187], v165 offset:1024
	ds_read_b128 v[188:191], v165 offset:2048
	ds_read_b128 v[192:195], v165 offset:3072
	s_add_u32 s40, s40, 0x80000
	s_addc_u32 s41, s41, 0
	s_mov_b32 m0, s50
	v_lshl_add_u64 v[246:247], s[40:41], 0, v[138:139]
	ds_read_b128 v[196:199], v164 offset:32768
	ds_read_b128 v[200:203], v164 offset:33792
	ds_read_b128 v[218:221], v164 offset:34816
	ds_read_b128 v[222:225], v164 offset:35840
	ds_read_b128 v[226:229], v164 offset:36864
	ds_read_b128 v[230:233], v164 offset:37888
	ds_read_b128 v[234:237], v164 offset:38912
	ds_read_b128 v[238:241], v164 offset:39936
	global_load_lds_dwordx4 v[246:247], off
	v_lshl_add_u64 v[246:247], s[40:41], 0, v[136:137]
	s_mov_b32 m0, s51
	s_nop 0
	global_load_lds_dwordx4 v[246:247], off
	s_waitcnt vmcnt(8)
	s_waitcnt lgkmcnt(0)
	s_barrier
	v_mfma_f32_16x16x32_bf16 v[126:129], v[130:133], v[196:199], v[126:129]
	v_mfma_f32_16x16x32_bf16 v[118:121], v[150:153], v[196:199], v[118:121]
	v_mfma_f32_16x16x32_bf16 v[110:113], v[130:133], v[218:221], v[110:113]
	v_mfma_f32_16x16x32_bf16 v[102:105], v[150:153], v[218:221], v[102:105]
	v_mfma_f32_16x16x32_bf16 v[94:97], v[130:133], v[226:229], v[94:97]
	v_mfma_f32_16x16x32_bf16 v[86:89], v[150:153], v[226:229], v[86:89]
	v_mfma_f32_16x16x32_bf16 v[78:81], v[130:133], v[234:237], v[78:81]
	v_mfma_f32_16x16x32_bf16 v[70:73], v[150:153], v[234:237], v[70:73]
	v_mfma_f32_16x16x32_bf16 v[126:129], v[146:149], v[200:203], v[126:129]
	v_mfma_f32_16x16x32_bf16 v[118:121], v[154:157], v[200:203], v[118:121]
	v_mfma_f32_16x16x32_bf16 v[110:113], v[146:149], v[222:225], v[110:113]
	v_mfma_f32_16x16x32_bf16 v[102:105], v[154:157], v[222:225], v[102:105]
	v_mfma_f32_16x16x32_bf16 v[94:97], v[146:149], v[230:233], v[94:97]
	v_mfma_f32_16x16x32_bf16 v[86:89], v[154:157], v[230:233], v[86:89]
	v_mfma_f32_16x16x32_bf16 v[78:81], v[146:149], v[238:241], v[78:81]
	v_mfma_f32_16x16x32_bf16 v[70:73], v[154:157], v[238:241], v[70:73]
	v_mfma_f32_16x16x32_bf16 v[122:125], v[180:183], v[196:199], v[122:125]
	v_mfma_f32_16x16x32_bf16 v[114:117], v[188:191], v[196:199], v[114:117]
	v_mfma_f32_16x16x32_bf16 v[106:109], v[180:183], v[218:221], v[106:109]
	v_mfma_f32_16x16x32_bf16 v[98:101], v[188:191], v[218:221], v[98:101]
	v_mfma_f32_16x16x32_bf16 v[90:93], v[180:183], v[226:229], v[90:93]
	v_mfma_f32_16x16x32_bf16 v[82:85], v[188:191], v[226:229], v[82:85]
	v_mfma_f32_16x16x32_bf16 v[74:77], v[180:183], v[234:237], v[74:77]
	v_mfma_f32_16x16x32_bf16 v[66:69], v[188:191], v[234:237], v[66:69]
	v_mfma_f32_16x16x32_bf16 v[122:125], v[184:187], v[200:203], v[122:125]
	v_mfma_f32_16x16x32_bf16 v[114:117], v[192:195], v[200:203], v[114:117]
	v_mfma_f32_16x16x32_bf16 v[106:109], v[184:187], v[222:225], v[106:109]
	v_mfma_f32_16x16x32_bf16 v[98:101], v[192:195], v[222:225], v[98:101]
	v_mfma_f32_16x16x32_bf16 v[90:93], v[184:187], v[230:233], v[90:93]
	v_mfma_f32_16x16x32_bf16 v[82:85], v[192:195], v[230:233], v[82:85]
	v_mfma_f32_16x16x32_bf16 v[74:77], v[184:187], v[238:241], v[74:77]
	v_mfma_f32_16x16x32_bf16 v[66:69], v[192:195], v[238:241], v[66:69]
	s_barrier
; #define PG8_STAGE(bufoff, gbase, voff) do { _Pragma("unroll") for (int _i = 0; _i < 2; ++_i) \
;         __builtin_amdgcn_global_load_lds((const unsigned*)((const char*)(gbase) + (voff)[_i]), (PG8_LAS unsigned*)(lds + (bufoff) + ldsw + _i * 8192), 16, 0, 0); } while (0)
; #define PG8_LDA(dst, b, h) do { _Pragma("unroll") for (int m = 0; m < 4; ++m) _Pragma("unroll") for (int k = 0; k < 2; ++k) dst[m][k] = *(const PG8_LAS bf16x8*)(lds + PG8_SA(b, h) + aoff + m * 2048 + k * 1024); } while (0)
; #define PG8_MMA(ai, bj, At, Bt) do { __builtin_amdgcn_s_setprio(1); _Pragma("unroll") for (int m = 0; m < 4; ++m) _Pragma("unroll") for (int n = 0; n < 2; ++n) _Pragma("unroll") for (int k = 0; k < 2; ++k) \
;         acc[ai][bj][m][n] = __builtin_amdgcn_mfma_f32_16x16x32_bf16(Bt[n][k], At[m][k], acc[ai][bj][m][n], 0, 0, 0); __builtin_amdgcn_s_setprio(0); } while (0)
; #define PG8_WAIT_V(n) asm volatile("s_waitcnt vmcnt(" #n ")" ::: "memory")
; #define PG8_WAIT_L(n) asm volatile("s_waitcnt lgkmcnt(" #n ")" ::: "memory")
; #define PG8_BAR __builtin_amdgcn_s_barrier()
; #define PG8_SCHED __builtin_amdgcn_sched_barrier(0)
; template <class Epi, class Sched, bool ALIGN_EPI = false, bool SP2 = false>
; __device__ __forceinline__ void gemm_phase(PG8_LAS unsigned char* lds, const Gemm g, const Sched& S, const Epi& E) {
;     ...
;         for (int t = 0; t < nt; t += 2) {
;     ...
;             PG8_LDA(At, 1, 1); PG8_STAGE(PG8_SB(1, 0), b3, voffB); PG8_STAGE(PG8_SB(1, 1), b3 + hstep, voffB); PG8_STAGE(PG8_SA(1, 0), a3, voffA);
;             PG8_WAIT_V(8); PG8_WAIT_L(0); PG8_BAR; PG8_MMA(1, 0, At, B0); PG8_MMA(1, 1, At, B1); PG8_BAR; PG8_SCHED;
	s_add_i32 s40, s78, s46
	v_lshl_add_u64 v[158:159], v[158:159], 0, s[34:35]
	s_mov_b32 m0, s40
	ds_read_b128 v[196:199], v164 offset:49152
	ds_read_b128 v[200:203], v164 offset:50176
	ds_read_b128 v[218:221], v164 offset:51200
	ds_read_b128 v[222:225], v164 offset:52224
	ds_read_b128 v[226:229], v164 offset:53248
	ds_read_b128 v[230:233], v164 offset:54272
	ds_read_b128 v[234:237], v164 offset:55296
	ds_read_b128 v[238:241], v164 offset:56320
	global_load_lds_dwordx4 v[158:159], off
	s_add_i32 m0, s40, 0x2000
	s_add_u32 s28, s28, 0x80080
	v_lshl_add_u64 v[158:159], v[166:167], 0, s[34:35]
	s_addc_u32 s29, s29, 0
	s_add_i32 s40, s80, s46
	global_load_lds_dwordx4 v[158:159], off
	v_lshl_add_u64 v[158:159], s[28:29], 0, v[0:1]
	s_mov_b32 m0, s40
	s_nop 0
	global_load_lds_dwordx4 v[158:159], off
	v_lshl_add_u64 v[158:159], s[28:29], 0, v[134:135]
	s_add_i32 m0, s40, 0x2000
	s_nop 0
	global_load_lds_dwordx4 v[158:159], off
	v_lshl_add_u64 v[158:159], v[242:243], 0, s[34:35]
	s_mov_b32 m0, s4
	s_nop 0
	global_load_lds_dwordx4 v[158:159], off
	v_lshl_add_u64 v[158:159], v[244:245], 0, s[34:35]
	s_mov_b32 m0, s52
	s_nop 0
	global_load_lds_dwordx4 v[158:159], off
	s_waitcnt vmcnt(8)
	s_waitcnt lgkmcnt(0)
	s_barrier
	v_mfma_f32_16x16x32_bf16 v[62:65], v[130:133], v[196:199], v[62:65]
	v_mfma_f32_16x16x32_bf16 v[54:57], v[150:153], v[196:199], v[54:57]
	v_mfma_f32_16x16x32_bf16 v[46:49], v[130:133], v[218:221], v[46:49]
	v_mfma_f32_16x16x32_bf16 v[38:41], v[150:153], v[218:221], v[38:41]
	v_mfma_f32_16x16x32_bf16 v[30:33], v[130:133], v[226:229], v[30:33]
	v_mfma_f32_16x16x32_bf16 v[22:25], v[150:153], v[226:229], v[22:25]
	v_mfma_f32_16x16x32_bf16 v[14:17], v[130:133], v[234:237], v[14:17]
	v_mfma_f32_16x16x32_bf16 v[6:9], v[150:153], v[234:237], v[6:9]
	v_mfma_f32_16x16x32_bf16 v[62:65], v[146:149], v[200:203], v[62:65]
	v_mfma_f32_16x16x32_bf16 v[54:57], v[154:157], v[200:203], v[54:57]
	v_mfma_f32_16x16x32_bf16 v[46:49], v[146:149], v[222:225], v[46:49]
	v_mfma_f32_16x16x32_bf16 v[38:41], v[154:157], v[222:225], v[38:41]
	v_mfma_f32_16x16x32_bf16 v[30:33], v[146:149], v[230:233], v[30:33]
	v_mfma_f32_16x16x32_bf16 v[22:25], v[154:157], v[230:233], v[22:25]
	v_mfma_f32_16x16x32_bf16 v[14:17], v[146:149], v[238:241], v[14:17]
	v_mfma_f32_16x16x32_bf16 v[6:9], v[154:157], v[238:241], v[6:9]
	v_mfma_f32_16x16x32_bf16 v[58:61], v[180:183], v[196:199], v[58:61]
	v_mfma_f32_16x16x32_bf16 v[50:53], v[188:191], v[196:199], v[50:53]
	v_mfma_f32_16x16x32_bf16 v[42:45], v[180:183], v[218:221], v[42:45]
	v_mfma_f32_16x16x32_bf16 v[34:37], v[188:191], v[218:221], v[34:37]
	v_mfma_f32_16x16x32_bf16 v[26:29], v[180:183], v[226:229], v[26:29]
	v_mfma_f32_16x16x32_bf16 v[18:21], v[188:191], v[226:229], v[18:21]
	v_mfma_f32_16x16x32_bf16 v[10:13], v[180:183], v[234:237], v[10:13]
	v_mfma_f32_16x16x32_bf16 v[2:5], v[188:191], v[234:237], v[2:5]
	v_mfma_f32_16x16x32_bf16 v[58:61], v[184:187], v[200:203], v[58:61]
	v_mfma_f32_16x16x32_bf16 v[50:53], v[192:195], v[200:203], v[50:53]
	v_mfma_f32_16x16x32_bf16 v[42:45], v[184:187], v[222:225], v[42:45]
	v_mfma_f32_16x16x32_bf16 v[34:37], v[192:195], v[222:225], v[34:37]
	v_mfma_f32_16x16x32_bf16 v[26:29], v[184:187], v[230:233], v[26:29]
	v_mfma_f32_16x16x32_bf16 v[18:21], v[192:195], v[230:233], v[18:21]
	v_mfma_f32_16x16x32_bf16 v[10:13], v[184:187], v[238:241], v[10:13]
	v_mfma_f32_16x16x32_bf16 v[2:5], v[192:195], v[238:241], v[2:5]
	s_barrier
	s_add_i32 s77, s77, 2
	s_add_u32 s26, s26, 0x100
	s_addc_u32 s27, s27, 0
	s_add_u32 s55, s55, 0x100
	s_addc_u32 s73, s73, 0
	s_cmp_gt_u32 s77, 29
	s_cbranch_scc0 .LBB0_165
	s_and_b64 vcc, exec, s[20:21]
	s_cbranch_vccz .LBB0_168
	s_barrier

; #define PG8_STAGE(bufoff, gbase, voff) do { _Pragma("unroll") for (int _i = 0; _i < 2; ++_i) \
;         __builtin_amdgcn_global_load_lds((const unsigned*)((const char*)(gbase) + (voff)[_i]), (PG8_LAS unsigned*)(lds + (bufoff) + ldsw + _i * 8192), 16, 0, 0); } while (0)
; #define PG8_LDA(dst, b, h) do { _Pragma("unroll") for (int m = 0; m < 4; ++m) _Pragma("unroll") for (int k = 0; k < 2; ++k) dst[m][k] = *(const PG8_LAS bf16x8*)(lds + PG8_SA(b, h) + aoff + m * 2048 + k * 1024); } while (0)
; #define PG8_LDB(dst, b, h) do { _Pragma("unroll") for (int n = 0; n < 2; ++n) _Pragma("unroll") for (int k = 0; k < 2; ++k) dst[n][k] = *(const PG8_LAS bf16x8*)(lds + PG8_SB(b, h) + boff + n * 2048 + k * 1024); } while (0)
; #define PG8_MMA(ai, bj, At, Bt) do { __builtin_amdgcn_s_setprio(1); _Pragma("unroll") for (int m = 0; m < 4; ++m) _Pragma("unroll") for (int n = 0; n < 2; ++n) _Pragma("unroll") for (int k = 0; k < 2; ++k) \
;         acc[ai][bj][m][n] = __builtin_amdgcn_mfma_f32_16x16x32_bf16(Bt[n][k], At[m][k], acc[ai][bj][m][n], 0, 0, 0); __builtin_amdgcn_s_setprio(0); } while (0)
; #define PG8_WAIT_V(n) asm volatile("s_waitcnt vmcnt(" #n ")" ::: "memory")
; #define PG8_WAIT_L(n) asm volatile("s_waitcnt lgkmcnt(" #n ")" ::: "memory")
; template <class Epi, class Sched, bool ALIGN_EPI = false, bool SP2 = false>
; __device__ __forceinline__ void gemm_phase(PG8_LAS unsigned char* lds, const Gemm g, const Sched& S, const Epi& E) {
;     ...
;             const bool last = (t == nt - 2);
;             const char* a1 = cA + (size_t)(t + 1) * kstep;
;             const char* a2 = last ? nA : cA + (size_t)(t + 2) * kstep; const char* b2 = last ? nB : cB + (size_t)(t + 2) * kstep;
;             const char* a3 = a2 + kstep; const char* b3 = b2 + kstep;
;             if (last && has_next) S.a_ready(nxt);
;             if constexpr (SP2) {
;             PG8_LDB(B0, 0, 0); PG8_LDB(B1, 0, 1); PG8_SCHED; PG8_LDA(At, 0, 0); PG8_STAGE(PG8_SA(1, 1), a1 + hstep, voffA);
;             PG8_WAIT_V(8); PG8_WAIT_L(0); PG8_BAR; PG8_MMA(0, 0, At, B0); PG8_MMA(0, 1, At, B1); PG8_BAR; PG8_SCHED;
;             PG8_LDA(At, 0, 1); PG8_STAGE(PG8_SB(0, 0), b2, voffB); PG8_STAGE(PG8_SB(0, 1), b2 + hstep, voffB); PG8_STAGE(PG8_SA(0, 0), a2, voffA);
;             PG8_WAIT_V(8); PG8_WAIT_L(0); PG8_BAR; PG8_MMA(1, 0, At, B0); PG8_MMA(1, 1, At, B1); PG8_BAR; PG8_SCHED;
.LBB0_429:
	s_add_u32 s26, s16, 0xfffc0080
	s_addc_u32 s27, s17, -1
	s_add_i32 s54, 0, 0x10000
	s_cmp_eq_u32 s78, 12
	s_cselect_b32 s29, s21, s27
	s_cselect_b32 s28, s52, s26
	v_add_u32_e32 v0, s54, v218
	s_cselect_b32 s27, s19, s77
	s_cselect_b32 s26, s53, s73
	s_add_i32 s55, 0, 0x14000
	ds_read_b128 v[52:55], v0
	ds_read_b128 v[56:59], v0 offset:1024
	ds_read_b128 v[92:95], v0 offset:2048
	ds_read_b128 v[96:99], v0 offset:3072
	v_add_u32_e32 v0, s55, v218
	ds_read_b128 v[124:127], v0
	ds_read_b128 v[128:131], v0 offset:1024
	ds_read_b128 v[148:151], v0 offset:2048
	ds_read_b128 v[152:155], v0 offset:3072
	v_lshl_add_u64 v[2:3], s[16:17], 0, v[188:189]
	s_add_i32 m0, s37, 0xc000
	ds_read_b128 v[164:167], v220
	ds_read_b128 v[192:195], v220 offset:1024
	ds_read_b128 v[196:199], v220 offset:2048
	ds_read_b128 v[200:203], v220 offset:3072
	ds_read_b128 v[222:225], v220 offset:4096
	ds_read_b128 v[226:229], v220 offset:5120
	ds_read_b128 v[230:233], v220 offset:6144
	ds_read_b128 v[234:237], v220 offset:7168
	global_load_lds_dwordx4 v[2:3], off
	v_lshl_add_u64 v[2:3], s[16:17], 0, v[190:191]
	s_add_i32 m0, s37, 0xe000
	s_nop 0
	global_load_lds_dwordx4 v[2:3], off
	s_waitcnt vmcnt(8)
	s_waitcnt lgkmcnt(0)
	s_barrier
	v_mfma_f32_16x16x32_bf16 v[88:91], v[52:55], v[164:167], v[88:91]
	v_mfma_f32_16x16x32_bf16 v[84:87], v[92:95], v[164:167], v[84:87]
	v_mfma_f32_16x16x32_bf16 v[120:123], v[52:55], v[196:199], v[120:123]
	v_mfma_f32_16x16x32_bf16 v[108:111], v[92:95], v[196:199], v[108:111]
	v_mfma_f32_16x16x32_bf16 v[136:139], v[52:55], v[222:225], v[136:139]
	v_mfma_f32_16x16x32_bf16 v[132:135], v[92:95], v[222:225], v[132:135]
	v_mfma_f32_16x16x32_bf16 v[104:107], v[52:55], v[230:233], v[104:107]
	v_mfma_f32_16x16x32_bf16 v[100:103], v[92:95], v[230:233], v[100:103]
	v_mfma_f32_16x16x32_bf16 v[88:91], v[56:59], v[192:195], v[88:91]
	v_mfma_f32_16x16x32_bf16 v[84:87], v[96:99], v[192:195], v[84:87]
	v_mfma_f32_16x16x32_bf16 v[120:123], v[56:59], v[200:203], v[120:123]
	v_mfma_f32_16x16x32_bf16 v[108:111], v[96:99], v[200:203], v[108:111]
	v_mfma_f32_16x16x32_bf16 v[136:139], v[56:59], v[226:229], v[136:139]
	v_mfma_f32_16x16x32_bf16 v[132:135], v[96:99], v[226:229], v[132:135]
	v_mfma_f32_16x16x32_bf16 v[104:107], v[56:59], v[234:237], v[104:107]
	v_mfma_f32_16x16x32_bf16 v[100:103], v[96:99], v[234:237], v[100:103]
	v_mfma_f32_16x16x32_bf16 v[160:163], v[124:127], v[164:167], v[160:163]
	v_mfma_f32_16x16x32_bf16 v[156:159], v[148:151], v[164:167], v[156:159]
	v_mfma_f32_16x16x32_bf16 v[144:147], v[124:127], v[196:199], v[144:147]
	v_mfma_f32_16x16x32_bf16 v[140:143], v[148:151], v[196:199], v[140:143]
	v_mfma_f32_16x16x32_bf16 v[116:119], v[124:127], v[222:225], v[116:119]
	v_mfma_f32_16x16x32_bf16 v[112:115], v[148:151], v[222:225], v[112:115]
	v_mfma_f32_16x16x32_bf16 v[80:83], v[124:127], v[230:233], v[80:83]
	v_mfma_f32_16x16x32_bf16 v[76:79], v[148:151], v[230:233], v[76:79]
	v_mfma_f32_16x16x32_bf16 v[160:163], v[128:131], v[192:195], v[160:163]
	v_mfma_f32_16x16x32_bf16 v[156:159], v[152:155], v[192:195], v[156:159]
	v_mfma_f32_16x16x32_bf16 v[144:147], v[128:131], v[200:203], v[144:147]
	v_mfma_f32_16x16x32_bf16 v[140:143], v[152:155], v[200:203], v[140:143]
	v_mfma_f32_16x16x32_bf16 v[116:119], v[128:131], v[226:229], v[116:119]
	v_mfma_f32_16x16x32_bf16 v[112:115], v[152:155], v[226:229], v[112:115]
	v_mfma_f32_16x16x32_bf16 v[80:83], v[128:131], v[234:237], v[80:83]
	v_mfma_f32_16x16x32_bf16 v[76:79], v[152:155], v[234:237], v[76:79]
	s_barrier
	s_add_i32 s54, s54, s2
	v_lshl_add_u64 v[238:239], s[26:27], 0, v[184:185]
	s_mov_b32 m0, s54
	ds_read_b128 v[164:167], v220 offset:16384
	ds_read_b128 v[192:195], v220 offset:17408
	ds_read_b128 v[196:199], v220 offset:18432
	ds_read_b128 v[200:203], v220 offset:19456
	ds_read_b128 v[222:225], v220 offset:20480
	ds_read_b128 v[226:229], v220 offset:21504
	ds_read_b128 v[230:233], v220 offset:22528
	ds_read_b128 v[234:237], v220 offset:23552
	global_load_lds_dwordx4 v[238:239], off
	s_add_i32 m0, s54, 0x2000
	s_add_u32 vcc_lo, s26, 0x40000
	v_lshl_add_u64 v[240:241], s[26:27], 0, v[180:181]
	s_addc_u32 vcc_hi, s27, 0
	s_add_i32 s54, s55, s2
	global_load_lds_dwordx4 v[240:241], off
	v_lshl_add_u64 v[2:3], vcc, 0, v[184:185]
	s_mov_b32 m0, s54
	v_lshl_add_u64 v[242:243], s[28:29], 0, v[186:187]
	global_load_lds_dwordx4 v[2:3], off
	v_lshl_add_u64 v[2:3], vcc, 0, v[180:181]
	s_add_i32 m0, s54, 0x2000
	v_lshl_add_u64 v[244:245], s[28:29], 0, v[182:183]
	global_load_lds_dwordx4 v[2:3], off
	s_mov_b32 m0, s37
	s_nop 0
	global_load_lds_dwordx4 v[242:243], off
	s_mov_b32 m0, s38
	s_nop 0
	global_load_lds_dwordx4 v[244:245], off
	s_waitcnt vmcnt(8)
	s_waitcnt lgkmcnt(0)
	s_barrier
; #define PG8_STAGE(bufoff, gbase, voff) do { _Pragma("unroll") for (int _i = 0; _i < 2; ++_i) \
;         __builtin_amdgcn_global_load_lds((const unsigned*)((const char*)(gbase) + (voff)[_i]), (PG8_LAS unsigned*)(lds + (bufoff) + ldsw + _i * 8192), 16, 0, 0); } while (0)
; #define PG8_LDA(dst, b, h) do { _Pragma("unroll") for (int m = 0; m < 4; ++m) _Pragma("unroll") for (int k = 0; k < 2; ++k) dst[m][k] = *(const PG8_LAS bf16x8*)(lds + PG8_SA(b, h) + aoff + m * 2048 + k * 1024); } while (0)
; #define PG8_LDB(dst, b, h) do { _Pragma("unroll") for (int n = 0; n < 2; ++n) _Pragma("unroll") for (int k = 0; k < 2; ++k) dst[n][k] = *(const PG8_LAS bf16x8*)(lds + PG8_SB(b, h) + boff + n * 2048 + k * 1024); } while (0)
; #define PG8_MMA(ai, bj, At, Bt) do { __builtin_amdgcn_s_setprio(1); _Pragma("unroll") for (int m = 0; m < 4; ++m) _Pragma("unroll") for (int n = 0; n < 2; ++n) _Pragma("unroll") for (int k = 0; k < 2; ++k) \
;         acc[ai][bj][m][n] = __builtin_amdgcn_mfma_f32_16x16x32_bf16(Bt[n][k], At[m][k], acc[ai][bj][m][n], 0, 0, 0); __builtin_amdgcn_s_setprio(0); } while (0)
; #define PG8_WAIT_V(n) asm volatile("s_waitcnt vmcnt(" #n ")" ::: "memory")
; #define PG8_WAIT_L(n) asm volatile("s_waitcnt lgkmcnt(" #n ")" ::: "memory")
; #define PG8_BAR __builtin_amdgcn_s_barrier()
; #define PG8_SCHED __builtin_amdgcn_sched_barrier(0)
; template <class Epi, class Sched, bool ALIGN_EPI = false, bool SP2 = false>
; __device__ __forceinline__ void gemm_phase(PG8_LAS unsigned char* lds, const Gemm g, const Sched& S, const Epi& E) {
;     ...
;             PG8_WAIT_V(8); PG8_WAIT_L(0); PG8_BAR; PG8_MMA(1, 0, At, B0); PG8_MMA(1, 1, At, B1); PG8_BAR; PG8_SCHED;
;             PG8_LDB(B0, 1, 0); PG8_LDB(B1, 1, 1); PG8_SCHED; PG8_LDA(At, 1, 0); PG8_STAGE(PG8_SA(0, 1), a2 + hstep, voffA);
;             PG8_WAIT_V(8); PG8_WAIT_L(0); PG8_BAR; PG8_MMA(0, 0, At, B0); PG8_MMA(0, 1, At, B1); PG8_BAR; PG8_SCHED;
	v_mfma_f32_16x16x32_bf16 v[72:75], v[52:55], v[164:167], v[72:75]
	v_mfma_f32_16x16x32_bf16 v[68:71], v[92:95], v[164:167], v[68:71]
	v_mfma_f32_16x16x32_bf16 v[48:51], v[52:55], v[196:199], v[48:51]
	v_mfma_f32_16x16x32_bf16 v[44:47], v[92:95], v[196:199], v[44:47]
	v_mfma_f32_16x16x32_bf16 v[32:35], v[52:55], v[222:225], v[32:35]
	v_mfma_f32_16x16x32_bf16 v[28:31], v[92:95], v[222:225], v[28:31]
	v_mfma_f32_16x16x32_bf16 v[16:19], v[52:55], v[230:233], v[16:19]
	v_mfma_f32_16x16x32_bf16 v[12:15], v[92:95], v[230:233], v[12:15]
	v_mfma_f32_16x16x32_bf16 v[72:75], v[56:59], v[192:195], v[72:75]
	v_mfma_f32_16x16x32_bf16 v[68:71], v[96:99], v[192:195], v[68:71]
	v_mfma_f32_16x16x32_bf16 v[48:51], v[56:59], v[200:203], v[48:51]
	v_mfma_f32_16x16x32_bf16 v[44:47], v[96:99], v[200:203], v[44:47]
	v_mfma_f32_16x16x32_bf16 v[32:35], v[56:59], v[226:229], v[32:35]
	v_mfma_f32_16x16x32_bf16 v[28:31], v[96:99], v[226:229], v[28:31]
	v_mfma_f32_16x16x32_bf16 v[16:19], v[56:59], v[234:237], v[16:19]
	v_mfma_f32_16x16x32_bf16 v[12:15], v[96:99], v[234:237], v[12:15]
	v_mfma_f32_16x16x32_bf16 v[40:43], v[124:127], v[196:199], v[40:43]
	v_mfma_f32_16x16x32_bf16 v[36:39], v[148:151], v[196:199], v[36:39]
	v_mfma_f32_16x16x32_bf16 v[24:27], v[124:127], v[222:225], v[24:27]
	v_mfma_f32_16x16x32_bf16 v[20:23], v[148:151], v[222:225], v[20:23]
	v_mfma_f32_16x16x32_bf16 v[8:11], v[124:127], v[230:233], v[8:11]
	v_mfma_f32_16x16x32_bf16 v[2:5], v[148:151], v[230:233], v[4:7]
	v_mfma_f32_16x16x32_bf16 v[52:55], v[124:127], v[164:167], v[64:67]
	v_mfma_f32_16x16x32_bf16 v[56:59], v[148:151], v[164:167], v[60:63]
	v_mfma_f32_16x16x32_bf16 v[40:43], v[128:131], v[200:203], v[40:43]
	v_mfma_f32_16x16x32_bf16 v[36:39], v[152:155], v[200:203], v[36:39]
	v_mfma_f32_16x16x32_bf16 v[24:27], v[128:131], v[226:229], v[24:27]
	v_mfma_f32_16x16x32_bf16 v[20:23], v[152:155], v[226:229], v[20:23]
	v_mfma_f32_16x16x32_bf16 v[8:11], v[128:131], v[234:237], v[8:11]
	v_mfma_f32_16x16x32_bf16 v[2:5], v[152:155], v[234:237], v[2:5]
	v_mfma_f32_16x16x32_bf16 v[52:55], v[128:131], v[192:195], v[52:55]
	v_mfma_f32_16x16x32_bf16 v[56:59], v[152:155], v[192:195], v[56:59]
	s_barrier
	s_add_i32 s54, 0, 0x18000
	v_add_u32_e32 v0, s54, v218
	s_add_i32 s55, 0, 0x1c000
	ds_read_b128 v[60:63], v0
	ds_read_b128 v[64:67], v0 offset:1024
	ds_read_b128 v[92:95], v0 offset:2048
	ds_read_b128 v[96:99], v0 offset:3072
	v_add_u32_e32 v0, s55, v218
	ds_read_b128 v[124:127], v0
	ds_read_b128 v[128:131], v0 offset:1024
	ds_read_b128 v[148:151], v0 offset:2048
	ds_read_b128 v[152:155], v0 offset:3072
	s_add_u32 s28, s28, 0x40000
	s_addc_u32 s29, s29, 0
	s_mov_b32 m0, s39
	v_lshl_add_u64 v[6:7], s[28:29], 0, v[186:187]
	ds_read_b128 v[164:167], v220 offset:32768
	ds_read_b128 v[192:195], v220 offset:33792
	ds_read_b128 v[196:199], v220 offset:34816
	ds_read_b128 v[200:203], v220 offset:35840
	ds_read_b128 v[222:225], v220 offset:36864
	ds_read_b128 v[226:229], v220 offset:37888
	ds_read_b128 v[230:233], v220 offset:38912
	ds_read_b128 v[234:237], v220 offset:39936
	global_load_lds_dwordx4 v[6:7], off
	v_lshl_add_u64 v[6:7], s[28:29], 0, v[182:183]
	s_mov_b32 m0, s44
	s_nop 0
	global_load_lds_dwordx4 v[6:7], off
	s_waitcnt vmcnt(8)
	s_waitcnt lgkmcnt(0)
	s_barrier
	v_mfma_f32_16x16x32_bf16 v[88:91], v[60:63], v[164:167], v[88:91]
	v_mfma_f32_16x16x32_bf16 v[84:87], v[92:95], v[164:167], v[84:87]
	v_mfma_f32_16x16x32_bf16 v[120:123], v[60:63], v[196:199], v[120:123]
	v_mfma_f32_16x16x32_bf16 v[108:111], v[92:95], v[196:199], v[108:111]
	v_mfma_f32_16x16x32_bf16 v[136:139], v[60:63], v[222:225], v[136:139]
	v_mfma_f32_16x16x32_bf16 v[132:135], v[92:95], v[222:225], v[132:135]
	v_mfma_f32_16x16x32_bf16 v[104:107], v[60:63], v[230:233], v[104:107]
	v_mfma_f32_16x16x32_bf16 v[100:103], v[92:95], v[230:233], v[100:103]
	v_mfma_f32_16x16x32_bf16 v[88:91], v[64:67], v[192:195], v[88:91]
	v_mfma_f32_16x16x32_bf16 v[84:87], v[96:99], v[192:195], v[84:87]
	v_mfma_f32_16x16x32_bf16 v[120:123], v[64:67], v[200:203], v[120:123]
	v_mfma_f32_16x16x32_bf16 v[108:111], v[96:99], v[200:203], v[108:111]
	v_mfma_f32_16x16x32_bf16 v[136:139], v[64:67], v[226:229], v[136:139]
	v_mfma_f32_16x16x32_bf16 v[132:135], v[96:99], v[226:229], v[132:135]
	v_mfma_f32_16x16x32_bf16 v[104:107], v[64:67], v[234:237], v[104:107]
	v_mfma_f32_16x16x32_bf16 v[100:103], v[96:99], v[234:237], v[100:103]
	v_mfma_f32_16x16x32_bf16 v[160:163], v[124:127], v[164:167], v[160:163]
	v_mfma_f32_16x16x32_bf16 v[156:159], v[148:151], v[164:167], v[156:159]
	v_mfma_f32_16x16x32_bf16 v[144:147], v[124:127], v[196:199], v[144:147]
	v_mfma_f32_16x16x32_bf16 v[140:143], v[148:151], v[196:199], v[140:143]
	v_mfma_f32_16x16x32_bf16 v[116:119], v[124:127], v[222:225], v[116:119]
	v_mfma_f32_16x16x32_bf16 v[112:115], v[148:151], v[222:225], v[112:115]
	v_mfma_f32_16x16x32_bf16 v[80:83], v[124:127], v[230:233], v[80:83]
	v_mfma_f32_16x16x32_bf16 v[76:79], v[148:151], v[230:233], v[76:79]
	v_mfma_f32_16x16x32_bf16 v[160:163], v[128:131], v[192:195], v[160:163]
	v_mfma_f32_16x16x32_bf16 v[156:159], v[152:155], v[192:195], v[156:159]
	v_mfma_f32_16x16x32_bf16 v[144:147], v[128:131], v[200:203], v[144:147]
	v_mfma_f32_16x16x32_bf16 v[140:143], v[152:155], v[200:203], v[140:143]
	v_mfma_f32_16x16x32_bf16 v[116:119], v[128:131], v[226:229], v[116:119]
	v_mfma_f32_16x16x32_bf16 v[112:115], v[152:155], v[226:229], v[112:115]
	v_mfma_f32_16x16x32_bf16 v[80:83], v[128:131], v[234:237], v[80:83]
	v_mfma_f32_16x16x32_bf16 v[76:79], v[152:155], v[234:237], v[76:79]
	s_barrier
; #define PG8_STAGE(bufoff, gbase, voff) do { _Pragma("unroll") for (int _i = 0; _i < 2; ++_i) \
;         __builtin_amdgcn_global_load_lds((const unsigned*)((const char*)(gbase) + (voff)[_i]), (PG8_LAS unsigned*)(lds + (bufoff) + ldsw + _i * 8192), 16, 0, 0); } while (0)
; #define PG8_LDA(dst, b, h) do { _Pragma("unroll") for (int m = 0; m < 4; ++m) _Pragma("unroll") for (int k = 0; k < 2; ++k) dst[m][k] = *(const PG8_LAS bf16x8*)(lds + PG8_SA(b, h) + aoff + m * 2048 + k * 1024); } while (0)
; #define PG8_MMA(ai, bj, At, Bt) do { __builtin_amdgcn_s_setprio(1); _Pragma("unroll") for (int m = 0; m < 4; ++m) _Pragma("unroll") for (int n = 0; n < 2; ++n) _Pragma("unroll") for (int k = 0; k < 2; ++k) \
;         acc[ai][bj][m][n] = __builtin_amdgcn_mfma_f32_16x16x32_bf16(Bt[n][k], At[m][k], acc[ai][bj][m][n], 0, 0, 0); __builtin_amdgcn_s_setprio(0); } while (0)
; #define PG8_WAIT_V(n) asm volatile("s_waitcnt vmcnt(" #n ")" ::: "memory")
; #define PG8_WAIT_L(n) asm volatile("s_waitcnt lgkmcnt(" #n ")" ::: "memory")
; #define PG8_BAR __builtin_amdgcn_s_barrier()
; #define PG8_SCHED __builtin_amdgcn_sched_barrier(0)
; template <class Epi, class Sched, bool ALIGN_EPI = false, bool SP2 = false>
; __device__ __forceinline__ void gemm_phase(PG8_LAS unsigned char* lds, const Gemm g, const Sched& S, const Epi& E) {
;     ...
;         for (int t = 0; t < nt; t += 2) {
;     ...
;             PG8_LDA(At, 1, 1); PG8_STAGE(PG8_SB(1, 0), b3, voffB); PG8_STAGE(PG8_SB(1, 1), b3 + hstep, voffB); PG8_STAGE(PG8_SA(1, 0), a3, voffA);
;             PG8_WAIT_V(8); PG8_WAIT_L(0); PG8_BAR; PG8_MMA(1, 0, At, B0); PG8_MMA(1, 1, At, B1); PG8_BAR; PG8_SCHED;
	s_add_i32 s28, s54, s2
	v_lshl_add_u64 v[6:7], v[238:239], 0, s[34:35]
	s_mov_b32 m0, s28
	ds_read_b128 v[164:167], v220 offset:49152
	ds_read_b128 v[192:195], v220 offset:50176
	ds_read_b128 v[196:199], v220 offset:51200
	ds_read_b128 v[200:203], v220 offset:52224
	ds_read_b128 v[222:225], v220 offset:53248
	ds_read_b128 v[226:229], v220 offset:54272
	ds_read_b128 v[230:233], v220 offset:55296
	ds_read_b128 v[234:237], v220 offset:56320
	global_load_lds_dwordx4 v[6:7], off
	s_add_i32 m0, s28, 0x2000
	s_add_u32 s26, s26, 0x40080
	v_lshl_add_u64 v[6:7], v[240:241], 0, s[34:35]
	s_addc_u32 s27, s27, 0
	s_add_i32 s28, s55, s2
	global_load_lds_dwordx4 v[6:7], off
	v_lshl_add_u64 v[6:7], s[26:27], 0, v[184:185]
	s_mov_b32 m0, s28
	s_nop 0
	global_load_lds_dwordx4 v[6:7], off
	v_lshl_add_u64 v[6:7], s[26:27], 0, v[180:181]
	s_add_i32 m0, s28, 0x2000
	s_nop 0
	global_load_lds_dwordx4 v[6:7], off
	v_lshl_add_u64 v[6:7], v[242:243], 0, s[34:35]
	s_mov_b32 m0, s47
	s_nop 0
	global_load_lds_dwordx4 v[6:7], off
	v_lshl_add_u64 v[6:7], v[244:245], 0, s[34:35]
	s_mov_b32 m0, s48
	s_nop 0
	global_load_lds_dwordx4 v[6:7], off
	s_waitcnt vmcnt(8)
	s_waitcnt lgkmcnt(0)
	s_barrier
	v_mfma_f32_16x16x32_bf16 v[72:75], v[60:63], v[164:167], v[72:75]
	v_mfma_f32_16x16x32_bf16 v[68:71], v[92:95], v[164:167], v[68:71]
	v_mfma_f32_16x16x32_bf16 v[48:51], v[60:63], v[196:199], v[48:51]
	v_mfma_f32_16x16x32_bf16 v[44:47], v[92:95], v[196:199], v[44:47]
	v_mfma_f32_16x16x32_bf16 v[32:35], v[60:63], v[222:225], v[32:35]
	v_mfma_f32_16x16x32_bf16 v[28:31], v[92:95], v[222:225], v[28:31]
	v_mfma_f32_16x16x32_bf16 v[16:19], v[60:63], v[230:233], v[16:19]
	v_mfma_f32_16x16x32_bf16 v[12:15], v[92:95], v[230:233], v[12:15]
	v_mfma_f32_16x16x32_bf16 v[72:75], v[64:67], v[192:195], v[72:75]
	v_mfma_f32_16x16x32_bf16 v[68:71], v[96:99], v[192:195], v[68:71]
	v_mfma_f32_16x16x32_bf16 v[48:51], v[64:67], v[200:203], v[48:51]
	v_mfma_f32_16x16x32_bf16 v[44:47], v[96:99], v[200:203], v[44:47]
	v_mfma_f32_16x16x32_bf16 v[32:35], v[64:67], v[226:229], v[32:35]
	v_mfma_f32_16x16x32_bf16 v[28:31], v[96:99], v[226:229], v[28:31]
	v_mfma_f32_16x16x32_bf16 v[16:19], v[64:67], v[234:237], v[16:19]
	v_mfma_f32_16x16x32_bf16 v[12:15], v[96:99], v[234:237], v[12:15]
	v_mfma_f32_16x16x32_bf16 v[52:55], v[124:127], v[164:167], v[52:55]
	v_mfma_f32_16x16x32_bf16 v[64:67], v[128:131], v[192:195], v[52:55]
	v_mfma_f32_16x16x32_bf16 v[52:55], v[148:151], v[164:167], v[56:59]
	v_mfma_f32_16x16x32_bf16 v[40:43], v[124:127], v[196:199], v[40:43]
	v_mfma_f32_16x16x32_bf16 v[36:39], v[148:151], v[196:199], v[36:39]
	v_mfma_f32_16x16x32_bf16 v[24:27], v[124:127], v[222:225], v[24:27]
	v_mfma_f32_16x16x32_bf16 v[20:23], v[148:151], v[222:225], v[20:23]
	v_mfma_f32_16x16x32_bf16 v[6:9], v[124:127], v[230:233], v[8:11]
	v_mfma_f32_16x16x32_bf16 v[2:5], v[148:151], v[230:233], v[2:5]
	v_mfma_f32_16x16x32_bf16 v[60:63], v[152:155], v[192:195], v[52:55]
	v_mfma_f32_16x16x32_bf16 v[40:43], v[128:131], v[200:203], v[40:43]
	v_mfma_f32_16x16x32_bf16 v[36:39], v[152:155], v[200:203], v[36:39]
	v_mfma_f32_16x16x32_bf16 v[24:27], v[128:131], v[226:229], v[24:27]
	v_mfma_f32_16x16x32_bf16 v[20:23], v[152:155], v[226:229], v[20:23]
	v_mfma_f32_16x16x32_bf16 v[8:11], v[128:131], v[234:237], v[6:9]
	v_mfma_f32_16x16x32_bf16 v[4:7], v[152:155], v[234:237], v[2:5]
	s_barrier
	s_add_i32 s78, s78, 2
	s_add_u32 s16, s16, 0x100
	s_addc_u32 s17, s17, 0
	s_add_u32 s73, s73, 0x100
	s_addc_u32 s77, s77, 0
	s_cmp_gt_u32 s78, 13
	s_cbranch_scc0 .LBB0_429
	s_and_b64 vcc, exec, s[6:7]
	s_cbranch_vccz .LBB0_432
	s_barrier

; #define PG8_STAGE(bufoff, gbase, voff) do { _Pragma("unroll") for (int _i = 0; _i < 2; ++_i) \
;         __builtin_amdgcn_global_load_lds((const unsigned*)((const char*)(gbase) + (voff)[_i]), (PG8_LAS unsigned*)(lds + (bufoff) + ldsw + _i * 8192), 16, 0, 0); } while (0)
; #define PG8_LDA(dst, b, h) do { _Pragma("unroll") for (int m = 0; m < 4; ++m) _Pragma("unroll") for (int k = 0; k < 2; ++k) dst[m][k] = *(const PG8_LAS bf16x8*)(lds + PG8_SA(b, h) + aoff + m * 2048 + k * 1024); } while (0)
; #define PG8_LDB(dst, b, h) do { _Pragma("unroll") for (int n = 0; n < 2; ++n) _Pragma("unroll") for (int k = 0; k < 2; ++k) dst[n][k] = *(const PG8_LAS bf16x8*)(lds + PG8_SB(b, h) + boff + n * 2048 + k * 1024); } while (0)
; #define PG8_MMA(ai, bj, At, Bt) do { __builtin_amdgcn_s_setprio(1); _Pragma("unroll") for (int m = 0; m < 4; ++m) _Pragma("unroll") for (int n = 0; n < 2; ++n) _Pragma("unroll") for (int k = 0; k < 2; ++k) \
;         acc[ai][bj][m][n] = __builtin_amdgcn_mfma_f32_16x16x32_bf16(Bt[n][k], At[m][k], acc[ai][bj][m][n], 0, 0, 0); __builtin_amdgcn_s_setprio(0); } while (0)
; #define PG8_WAIT_V(n) asm volatile("s_waitcnt vmcnt(" #n ")" ::: "memory")
; #define PG8_WAIT_L(n) asm volatile("s_waitcnt lgkmcnt(" #n ")" ::: "memory")
; template <class Epi, class Sched, bool ALIGN_EPI = false, bool SP2 = false>
; __device__ __forceinline__ void gemm_phase(PG8_LAS unsigned char* lds, const Gemm g, const Sched& S, const Epi& E) {
;     ...
;             const bool last = (t == nt - 2);
;             const char* a1 = cA + (size_t)(t + 1) * kstep;
;             const char* a2 = last ? nA : cA + (size_t)(t + 2) * kstep; const char* b2 = last ? nB : cB + (size_t)(t + 2) * kstep;
;             const char* a3 = a2 + kstep; const char* b3 = b2 + kstep;
;             if (last && has_next) S.a_ready(nxt);
;             if constexpr (SP2) {
;             PG8_LDB(B0, 0, 0); PG8_LDB(B1, 0, 1); PG8_SCHED; PG8_LDA(At, 0, 0); PG8_STAGE(PG8_SA(1, 1), a1 + hstep, voffA);
;             PG8_WAIT_V(8); PG8_WAIT_L(0); PG8_BAR; PG8_MMA(0, 0, At, B0); PG8_MMA(0, 1, At, B1); PG8_BAR; PG8_SCHED;
;             PG8_LDA(At, 0, 1); PG8_STAGE(PG8_SB(0, 0), b2, voffB); PG8_STAGE(PG8_SB(0, 1), b2 + hstep, voffB); PG8_STAGE(PG8_SA(0, 0), a2, voffA);
;             PG8_WAIT_V(8); PG8_WAIT_L(0); PG8_BAR; PG8_MMA(1, 0, At, B0); PG8_MMA(1, 1, At, B1); PG8_BAR; PG8_SCHED;
.LBB0_553:
	s_add_u32 s26, s16, 0xfff80080
	s_addc_u32 s27, s17, -1
	s_add_i32 s54, 0, 0x10000
	s_cmp_eq_u32 vcc_hi, 28
	s_cselect_b32 s29, s23, s27
	s_cselect_b32 s28, s38, s26
	s_cselect_b32 s27, s21, vcc_lo
	s_cselect_b32 s26, s39, s78
	s_add_i32 s80, 0, 0x14000
	v_add_u32_e32 v134, s54, v191
	v_add_u32_e32 v166, s80, v191
	ds_read_b128 v[114:117], v134
	ds_read_b128 v[118:121], v134 offset:1024
	ds_read_b128 v[122:125], v134 offset:2048
	ds_read_b128 v[134:137], v134 offset:3072
	ds_read_b128 v[146:149], v166
	ds_read_b128 v[150:153], v166 offset:1024
	ds_read_b128 v[180:183], v166 offset:2048
	ds_read_b128 v[184:187], v166 offset:3072
	v_lshl_add_u64 v[166:167], s[16:17], 0, v[162:163]
	s_add_i32 m0, s48, 0xc000
	ds_read_b128 v[196:199], v194
	ds_read_b128 v[200:203], v194 offset:1024
	ds_read_b128 v[218:221], v194 offset:2048
	ds_read_b128 v[222:225], v194 offset:3072
	ds_read_b128 v[226:229], v194 offset:4096
	ds_read_b128 v[230:233], v194 offset:5120
	ds_read_b128 v[234:237], v194 offset:6144
	ds_read_b128 v[238:241], v194 offset:7168
	global_load_lds_dwordx4 v[166:167], off
	v_lshl_add_u64 v[166:167], s[16:17], 0, v[164:165]
	s_add_i32 m0, s48, 0xe000
	s_nop 0
	global_load_lds_dwordx4 v[166:167], off
	s_waitcnt vmcnt(8)
	s_waitcnt lgkmcnt(0)
	s_barrier
	v_mfma_f32_16x16x32_bf16 v[142:145], v[114:117], v[196:199], v[142:145]
	v_mfma_f32_16x16x32_bf16 v[138:141], v[122:125], v[196:199], v[138:141]
	v_mfma_f32_16x16x32_bf16 v[110:113], v[114:117], v[218:221], v[110:113]
	v_mfma_f32_16x16x32_bf16 v[106:109], v[122:125], v[218:221], v[106:109]
	v_mfma_f32_16x16x32_bf16 v[94:97], v[114:117], v[226:229], v[94:97]
	v_mfma_f32_16x16x32_bf16 v[90:93], v[122:125], v[226:229], v[90:93]
	v_mfma_f32_16x16x32_bf16 v[78:81], v[114:117], v[234:237], v[78:81]
	v_mfma_f32_16x16x32_bf16 v[74:77], v[122:125], v[234:237], v[74:77]
	v_mfma_f32_16x16x32_bf16 v[142:145], v[118:121], v[200:203], v[142:145]
	v_mfma_f32_16x16x32_bf16 v[138:141], v[134:137], v[200:203], v[138:141]
	v_mfma_f32_16x16x32_bf16 v[110:113], v[118:121], v[222:225], v[110:113]
	v_mfma_f32_16x16x32_bf16 v[106:109], v[134:137], v[222:225], v[106:109]
	v_mfma_f32_16x16x32_bf16 v[94:97], v[118:121], v[230:233], v[94:97]
	v_mfma_f32_16x16x32_bf16 v[90:93], v[134:137], v[230:233], v[90:93]
	v_mfma_f32_16x16x32_bf16 v[78:81], v[118:121], v[238:241], v[78:81]
	v_mfma_f32_16x16x32_bf16 v[74:77], v[134:137], v[238:241], v[74:77]
	v_mfma_f32_16x16x32_bf16 v[130:133], v[146:149], v[196:199], v[130:133]
	v_mfma_f32_16x16x32_bf16 v[126:129], v[180:183], v[196:199], v[126:129]
	v_mfma_f32_16x16x32_bf16 v[102:105], v[146:149], v[218:221], v[102:105]
	v_mfma_f32_16x16x32_bf16 v[98:101], v[180:183], v[218:221], v[98:101]
	v_mfma_f32_16x16x32_bf16 v[86:89], v[146:149], v[226:229], v[86:89]
	v_mfma_f32_16x16x32_bf16 v[82:85], v[180:183], v[226:229], v[82:85]
	v_mfma_f32_16x16x32_bf16 v[70:73], v[146:149], v[234:237], v[70:73]
	v_mfma_f32_16x16x32_bf16 v[66:69], v[180:183], v[234:237], v[66:69]
	v_mfma_f32_16x16x32_bf16 v[130:133], v[150:153], v[200:203], v[130:133]
	v_mfma_f32_16x16x32_bf16 v[126:129], v[184:187], v[200:203], v[126:129]
	v_mfma_f32_16x16x32_bf16 v[102:105], v[150:153], v[222:225], v[102:105]
	v_mfma_f32_16x16x32_bf16 v[98:101], v[184:187], v[222:225], v[98:101]
	v_mfma_f32_16x16x32_bf16 v[86:89], v[150:153], v[230:233], v[86:89]
	v_mfma_f32_16x16x32_bf16 v[82:85], v[184:187], v[230:233], v[82:85]
	v_mfma_f32_16x16x32_bf16 v[70:73], v[150:153], v[238:241], v[70:73]
	v_mfma_f32_16x16x32_bf16 v[66:69], v[184:187], v[238:241], v[66:69]
	s_barrier
	s_add_i32 s54, s54, s2
	v_lshl_add_u64 v[166:167], s[26:27], 0, v[0:1]
	s_mov_b32 m0, s54
	ds_read_b128 v[196:199], v194 offset:16384
	ds_read_b128 v[200:203], v194 offset:17408
	ds_read_b128 v[218:221], v194 offset:18432
	ds_read_b128 v[222:225], v194 offset:19456
	ds_read_b128 v[226:229], v194 offset:20480
	ds_read_b128 v[230:233], v194 offset:21504
	ds_read_b128 v[234:237], v194 offset:22528
	ds_read_b128 v[238:241], v194 offset:23552
	global_load_lds_dwordx4 v[166:167], off
	s_add_i32 m0, s54, 0x2000
	s_add_u32 s54, s26, 0x80000
	v_lshl_add_u64 v[188:189], s[26:27], 0, v[154:155]
	s_addc_u32 s55, s27, 0
	s_add_i32 s80, s80, s2
	global_load_lds_dwordx4 v[188:189], off
	v_lshl_add_u64 v[242:243], s[54:55], 0, v[0:1]
	s_mov_b32 m0, s80
	v_lshl_add_u64 v[244:245], s[28:29], 0, v[156:157]
	global_load_lds_dwordx4 v[242:243], off
	v_lshl_add_u64 v[242:243], s[54:55], 0, v[154:155]
	s_add_i32 m0, s80, 0x2000
	s_nop 0
	global_load_lds_dwordx4 v[242:243], off
	v_lshl_add_u64 v[242:243], s[28:29], 0, v[158:159]
	s_mov_b32 m0, s48
	s_nop 0
	global_load_lds_dwordx4 v[242:243], off
	s_mov_b32 m0, s49
	s_nop 0
	global_load_lds_dwordx4 v[244:245], off
	s_waitcnt vmcnt(8)
	s_waitcnt lgkmcnt(0)
	s_barrier
; #define PG8_STAGE(bufoff, gbase, voff) do { _Pragma("unroll") for (int _i = 0; _i < 2; ++_i) \
;         __builtin_amdgcn_global_load_lds((const unsigned*)((const char*)(gbase) + (voff)[_i]), (PG8_LAS unsigned*)(lds + (bufoff) + ldsw + _i * 8192), 16, 0, 0); } while (0)
; #define PG8_LDA(dst, b, h) do { _Pragma("unroll") for (int m = 0; m < 4; ++m) _Pragma("unroll") for (int k = 0; k < 2; ++k) dst[m][k] = *(const PG8_LAS bf16x8*)(lds + PG8_SA(b, h) + aoff + m * 2048 + k * 1024); } while (0)
; #define PG8_LDB(dst, b, h) do { _Pragma("unroll") for (int n = 0; n < 2; ++n) _Pragma("unroll") for (int k = 0; k < 2; ++k) dst[n][k] = *(const PG8_LAS bf16x8*)(lds + PG8_SB(b, h) + boff + n * 2048 + k * 1024); } while (0)
; #define PG8_MMA(ai, bj, At, Bt) do { __builtin_amdgcn_s_setprio(1); _Pragma("unroll") for (int m = 0; m < 4; ++m) _Pragma("unroll") for (int n = 0; n < 2; ++n) _Pragma("unroll") for (int k = 0; k < 2; ++k) \
;         acc[ai][bj][m][n] = __builtin_amdgcn_mfma_f32_16x16x32_bf16(Bt[n][k], At[m][k], acc[ai][bj][m][n], 0, 0, 0); __builtin_amdgcn_s_setprio(0); } while (0)
; #define PG8_WAIT_V(n) asm volatile("s_waitcnt vmcnt(" #n ")" ::: "memory")
; #define PG8_WAIT_L(n) asm volatile("s_waitcnt lgkmcnt(" #n ")" ::: "memory")
; #define PG8_BAR __builtin_amdgcn_s_barrier()
; #define PG8_SCHED __builtin_amdgcn_sched_barrier(0)
; template <class Epi, class Sched, bool ALIGN_EPI = false, bool SP2 = false>
; __device__ __forceinline__ void gemm_phase(PG8_LAS unsigned char* lds, const Gemm g, const Sched& S, const Epi& E) {
;     ...
;             PG8_WAIT_V(8); PG8_WAIT_L(0); PG8_BAR; PG8_MMA(1, 0, At, B0); PG8_MMA(1, 1, At, B1); PG8_BAR; PG8_SCHED;
;             PG8_LDB(B0, 1, 0); PG8_LDB(B1, 1, 1); PG8_SCHED; PG8_LDA(At, 1, 0); PG8_STAGE(PG8_SA(0, 1), a2 + hstep, voffA);
;             PG8_WAIT_V(8); PG8_WAIT_L(0); PG8_BAR; PG8_MMA(0, 0, At, B0); PG8_MMA(0, 1, At, B1); PG8_BAR; PG8_SCHED;
	v_mfma_f32_16x16x32_bf16 v[62:65], v[114:117], v[196:199], v[62:65]
	v_mfma_f32_16x16x32_bf16 v[58:61], v[122:125], v[196:199], v[58:61]
	v_mfma_f32_16x16x32_bf16 v[46:49], v[114:117], v[218:221], v[46:49]
	v_mfma_f32_16x16x32_bf16 v[42:45], v[122:125], v[218:221], v[42:45]
	v_mfma_f32_16x16x32_bf16 v[30:33], v[114:117], v[226:229], v[30:33]
	v_mfma_f32_16x16x32_bf16 v[26:29], v[122:125], v[226:229], v[26:29]
	v_mfma_f32_16x16x32_bf16 v[14:17], v[114:117], v[234:237], v[14:17]
	v_mfma_f32_16x16x32_bf16 v[10:13], v[122:125], v[234:237], v[10:13]
	v_mfma_f32_16x16x32_bf16 v[62:65], v[118:121], v[200:203], v[62:65]
	v_mfma_f32_16x16x32_bf16 v[58:61], v[134:137], v[200:203], v[58:61]
	v_mfma_f32_16x16x32_bf16 v[46:49], v[118:121], v[222:225], v[46:49]
	v_mfma_f32_16x16x32_bf16 v[42:45], v[134:137], v[222:225], v[42:45]
	v_mfma_f32_16x16x32_bf16 v[30:33], v[118:121], v[230:233], v[30:33]
	v_mfma_f32_16x16x32_bf16 v[26:29], v[134:137], v[230:233], v[26:29]
	v_mfma_f32_16x16x32_bf16 v[14:17], v[118:121], v[238:241], v[14:17]
	v_mfma_f32_16x16x32_bf16 v[10:13], v[134:137], v[238:241], v[10:13]
	v_mfma_f32_16x16x32_bf16 v[54:57], v[146:149], v[196:199], v[54:57]
	v_mfma_f32_16x16x32_bf16 v[50:53], v[180:183], v[196:199], v[50:53]
	v_mfma_f32_16x16x32_bf16 v[38:41], v[146:149], v[218:221], v[38:41]
	v_mfma_f32_16x16x32_bf16 v[34:37], v[180:183], v[218:221], v[34:37]
	v_mfma_f32_16x16x32_bf16 v[22:25], v[146:149], v[226:229], v[22:25]
	v_mfma_f32_16x16x32_bf16 v[18:21], v[180:183], v[226:229], v[18:21]
	v_mfma_f32_16x16x32_bf16 v[6:9], v[146:149], v[234:237], v[6:9]
	v_mfma_f32_16x16x32_bf16 v[2:5], v[180:183], v[234:237], v[2:5]
	v_mfma_f32_16x16x32_bf16 v[54:57], v[150:153], v[200:203], v[54:57]
	v_mfma_f32_16x16x32_bf16 v[50:53], v[184:187], v[200:203], v[50:53]
	v_mfma_f32_16x16x32_bf16 v[38:41], v[150:153], v[222:225], v[38:41]
	v_mfma_f32_16x16x32_bf16 v[34:37], v[184:187], v[222:225], v[34:37]
	v_mfma_f32_16x16x32_bf16 v[22:25], v[150:153], v[230:233], v[22:25]
	v_mfma_f32_16x16x32_bf16 v[18:21], v[184:187], v[230:233], v[18:21]
	v_mfma_f32_16x16x32_bf16 v[6:9], v[150:153], v[238:241], v[6:9]
	v_mfma_f32_16x16x32_bf16 v[2:5], v[184:187], v[238:241], v[2:5]
	s_barrier
	s_add_i32 s54, 0, 0x18000
	s_add_i32 s55, 0, 0x1c000
	v_add_u32_e32 v134, s54, v191
	v_add_u32_e32 v184, s55, v191
	ds_read_b128 v[114:117], v134
	ds_read_b128 v[118:121], v134 offset:1024
	ds_read_b128 v[122:125], v134 offset:2048
	ds_read_b128 v[134:137], v134 offset:3072
	ds_read_b128 v[146:149], v184
	ds_read_b128 v[150:153], v184 offset:1024
	ds_read_b128 v[180:183], v184 offset:2048
	ds_read_b128 v[184:187], v184 offset:3072
	s_add_u32 s28, s28, 0x80000
	s_addc_u32 s29, s29, 0
	s_mov_b32 m0, s50
	v_lshl_add_u64 v[246:247], s[28:29], 0, v[158:159]
	ds_read_b128 v[196:199], v194 offset:32768
	ds_read_b128 v[200:203], v194 offset:33792
	ds_read_b128 v[218:221], v194 offset:34816
	ds_read_b128 v[222:225], v194 offset:35840
	ds_read_b128 v[226:229], v194 offset:36864
	ds_read_b128 v[230:233], v194 offset:37888
	ds_read_b128 v[234:237], v194 offset:38912
	ds_read_b128 v[238:241], v194 offset:39936
	global_load_lds_dwordx4 v[246:247], off
	v_lshl_add_u64 v[246:247], s[28:29], 0, v[156:157]
	s_mov_b32 m0, s51
	s_nop 0
	global_load_lds_dwordx4 v[246:247], off
	s_waitcnt vmcnt(8)
	s_waitcnt lgkmcnt(0)
	s_barrier
	v_mfma_f32_16x16x32_bf16 v[142:145], v[114:117], v[196:199], v[142:145]
	v_mfma_f32_16x16x32_bf16 v[138:141], v[122:125], v[196:199], v[138:141]
	v_mfma_f32_16x16x32_bf16 v[110:113], v[114:117], v[218:221], v[110:113]
	v_mfma_f32_16x16x32_bf16 v[106:109], v[122:125], v[218:221], v[106:109]
	v_mfma_f32_16x16x32_bf16 v[94:97], v[114:117], v[226:229], v[94:97]
	v_mfma_f32_16x16x32_bf16 v[90:93], v[122:125], v[226:229], v[90:93]
	v_mfma_f32_16x16x32_bf16 v[78:81], v[114:117], v[234:237], v[78:81]
	v_mfma_f32_16x16x32_bf16 v[74:77], v[122:125], v[234:237], v[74:77]
	v_mfma_f32_16x16x32_bf16 v[142:145], v[118:121], v[200:203], v[142:145]
	v_mfma_f32_16x16x32_bf16 v[138:141], v[134:137], v[200:203], v[138:141]
	v_mfma_f32_16x16x32_bf16 v[110:113], v[118:121], v[222:225], v[110:113]
	v_mfma_f32_16x16x32_bf16 v[106:109], v[134:137], v[222:225], v[106:109]
	v_mfma_f32_16x16x32_bf16 v[94:97], v[118:121], v[230:233], v[94:97]
	v_mfma_f32_16x16x32_bf16 v[90:93], v[134:137], v[230:233], v[90:93]
	v_mfma_f32_16x16x32_bf16 v[78:81], v[118:121], v[238:241], v[78:81]
	v_mfma_f32_16x16x32_bf16 v[74:77], v[134:137], v[238:241], v[74:77]
	v_mfma_f32_16x16x32_bf16 v[130:133], v[146:149], v[196:199], v[130:133]
	v_mfma_f32_16x16x32_bf16 v[126:129], v[180:183], v[196:199], v[126:129]
	v_mfma_f32_16x16x32_bf16 v[102:105], v[146:149], v[218:221], v[102:105]
	v_mfma_f32_16x16x32_bf16 v[98:101], v[180:183], v[218:221], v[98:101]
	v_mfma_f32_16x16x32_bf16 v[86:89], v[146:149], v[226:229], v[86:89]
	v_mfma_f32_16x16x32_bf16 v[82:85], v[180:183], v[226:229], v[82:85]
	v_mfma_f32_16x16x32_bf16 v[70:73], v[146:149], v[234:237], v[70:73]
	v_mfma_f32_16x16x32_bf16 v[66:69], v[180:183], v[234:237], v[66:69]
	v_mfma_f32_16x16x32_bf16 v[130:133], v[150:153], v[200:203], v[130:133]
	v_mfma_f32_16x16x32_bf16 v[126:129], v[184:187], v[200:203], v[126:129]
	v_mfma_f32_16x16x32_bf16 v[102:105], v[150:153], v[222:225], v[102:105]
	v_mfma_f32_16x16x32_bf16 v[98:101], v[184:187], v[222:225], v[98:101]
	v_mfma_f32_16x16x32_bf16 v[86:89], v[150:153], v[230:233], v[86:89]
	v_mfma_f32_16x16x32_bf16 v[82:85], v[184:187], v[230:233], v[82:85]
	v_mfma_f32_16x16x32_bf16 v[70:73], v[150:153], v[238:241], v[70:73]
	v_mfma_f32_16x16x32_bf16 v[66:69], v[184:187], v[238:241], v[66:69]
	s_barrier
; #define PG8_STAGE(bufoff, gbase, voff) do { _Pragma("unroll") for (int _i = 0; _i < 2; ++_i) \
;         __builtin_amdgcn_global_load_lds((const unsigned*)((const char*)(gbase) + (voff)[_i]), (PG8_LAS unsigned*)(lds + (bufoff) + ldsw + _i * 8192), 16, 0, 0); } while (0)
; #define PG8_LDA(dst, b, h) do { _Pragma("unroll") for (int m = 0; m < 4; ++m) _Pragma("unroll") for (int k = 0; k < 2; ++k) dst[m][k] = *(const PG8_LAS bf16x8*)(lds + PG8_SA(b, h) + aoff + m * 2048 + k * 1024); } while (0)
; #define PG8_MMA(ai, bj, At, Bt) do { __builtin_amdgcn_s_setprio(1); _Pragma("unroll") for (int m = 0; m < 4; ++m) _Pragma("unroll") for (int n = 0; n < 2; ++n) _Pragma("unroll") for (int k = 0; k < 2; ++k) \
;         acc[ai][bj][m][n] = __builtin_amdgcn_mfma_f32_16x16x32_bf16(Bt[n][k], At[m][k], acc[ai][bj][m][n], 0, 0, 0); __builtin_amdgcn_s_setprio(0); } while (0)
; #define PG8_WAIT_V(n) asm volatile("s_waitcnt vmcnt(" #n ")" ::: "memory")
; #define PG8_WAIT_L(n) asm volatile("s_waitcnt lgkmcnt(" #n ")" ::: "memory")
; #define PG8_BAR __builtin_amdgcn_s_barrier()
; #define PG8_SCHED __builtin_amdgcn_sched_barrier(0)
; template <class Epi, class Sched, bool ALIGN_EPI = false, bool SP2 = false>
; __device__ __forceinline__ void gemm_phase(PG8_LAS unsigned char* lds, const Gemm g, const Sched& S, const Epi& E) {
;     ...
;         for (int t = 0; t < nt; t += 2) {
;     ...
;             PG8_LDA(At, 1, 1); PG8_STAGE(PG8_SB(1, 0), b3, voffB); PG8_STAGE(PG8_SB(1, 1), b3 + hstep, voffB); PG8_STAGE(PG8_SA(1, 0), a3, voffA);
;             PG8_WAIT_V(8); PG8_WAIT_L(0); PG8_BAR; PG8_MMA(1, 0, At, B0); PG8_MMA(1, 1, At, B1); PG8_BAR; PG8_SCHED;
	s_add_i32 s28, s54, s2
	v_lshl_add_u64 v[166:167], v[166:167], 0, s[34:35]
	s_mov_b32 m0, s28
	ds_read_b128 v[196:199], v194 offset:49152
	ds_read_b128 v[200:203], v194 offset:50176
	ds_read_b128 v[218:221], v194 offset:51200
	ds_read_b128 v[222:225], v194 offset:52224
	ds_read_b128 v[226:229], v194 offset:53248
	ds_read_b128 v[230:233], v194 offset:54272
	ds_read_b128 v[234:237], v194 offset:55296
	ds_read_b128 v[238:241], v194 offset:56320
	global_load_lds_dwordx4 v[166:167], off
	s_add_i32 m0, s28, 0x2000
	s_add_u32 s26, s26, 0x80080
	v_lshl_add_u64 v[166:167], v[188:189], 0, s[34:35]
	s_addc_u32 s27, s27, 0
	s_add_i32 s28, s55, s2
	global_load_lds_dwordx4 v[166:167], off
	v_lshl_add_u64 v[166:167], s[26:27], 0, v[0:1]
	s_mov_b32 m0, s28
	s_nop 0
	global_load_lds_dwordx4 v[166:167], off
	v_lshl_add_u64 v[166:167], s[26:27], 0, v[154:155]
	s_add_i32 m0, s28, 0x2000
	s_nop 0
	global_load_lds_dwordx4 v[166:167], off
	v_lshl_add_u64 v[166:167], v[242:243], 0, s[34:35]
	s_mov_b32 m0, s53
	s_nop 0
	global_load_lds_dwordx4 v[166:167], off
	v_lshl_add_u64 v[166:167], v[244:245], 0, s[34:35]
	s_mov_b32 m0, s73
	s_nop 0
	global_load_lds_dwordx4 v[166:167], off
	s_waitcnt vmcnt(8)
	s_waitcnt lgkmcnt(0)
	s_barrier
	v_mfma_f32_16x16x32_bf16 v[62:65], v[114:117], v[196:199], v[62:65]
	v_mfma_f32_16x16x32_bf16 v[58:61], v[122:125], v[196:199], v[58:61]
	v_mfma_f32_16x16x32_bf16 v[46:49], v[114:117], v[218:221], v[46:49]
	v_mfma_f32_16x16x32_bf16 v[42:45], v[122:125], v[218:221], v[42:45]
	v_mfma_f32_16x16x32_bf16 v[30:33], v[114:117], v[226:229], v[30:33]
	v_mfma_f32_16x16x32_bf16 v[26:29], v[122:125], v[226:229], v[26:29]
	v_mfma_f32_16x16x32_bf16 v[14:17], v[114:117], v[234:237], v[14:17]
	v_mfma_f32_16x16x32_bf16 v[10:13], v[122:125], v[234:237], v[10:13]
	v_mfma_f32_16x16x32_bf16 v[62:65], v[118:121], v[200:203], v[62:65]
	v_mfma_f32_16x16x32_bf16 v[58:61], v[134:137], v[200:203], v[58:61]
	v_mfma_f32_16x16x32_bf16 v[46:49], v[118:121], v[222:225], v[46:49]
	v_mfma_f32_16x16x32_bf16 v[42:45], v[134:137], v[222:225], v[42:45]
	v_mfma_f32_16x16x32_bf16 v[30:33], v[118:121], v[230:233], v[30:33]
	v_mfma_f32_16x16x32_bf16 v[26:29], v[134:137], v[230:233], v[26:29]
	v_mfma_f32_16x16x32_bf16 v[14:17], v[118:121], v[238:241], v[14:17]
	v_mfma_f32_16x16x32_bf16 v[10:13], v[134:137], v[238:241], v[10:13]
	v_mfma_f32_16x16x32_bf16 v[54:57], v[146:149], v[196:199], v[54:57]
	v_mfma_f32_16x16x32_bf16 v[50:53], v[180:183], v[196:199], v[50:53]
	v_mfma_f32_16x16x32_bf16 v[38:41], v[146:149], v[218:221], v[38:41]
	v_mfma_f32_16x16x32_bf16 v[34:37], v[180:183], v[218:221], v[34:37]
	v_mfma_f32_16x16x32_bf16 v[22:25], v[146:149], v[226:229], v[22:25]
	v_mfma_f32_16x16x32_bf16 v[18:21], v[180:183], v[226:229], v[18:21]
	v_mfma_f32_16x16x32_bf16 v[6:9], v[146:149], v[234:237], v[6:9]
	v_mfma_f32_16x16x32_bf16 v[2:5], v[180:183], v[234:237], v[2:5]
	v_mfma_f32_16x16x32_bf16 v[54:57], v[150:153], v[200:203], v[54:57]
	v_mfma_f32_16x16x32_bf16 v[50:53], v[184:187], v[200:203], v[50:53]
	v_mfma_f32_16x16x32_bf16 v[38:41], v[150:153], v[222:225], v[38:41]
	v_mfma_f32_16x16x32_bf16 v[34:37], v[184:187], v[222:225], v[34:37]
	v_mfma_f32_16x16x32_bf16 v[22:25], v[150:153], v[230:233], v[22:25]
	v_mfma_f32_16x16x32_bf16 v[18:21], v[184:187], v[230:233], v[18:21]
	v_mfma_f32_16x16x32_bf16 v[6:9], v[150:153], v[238:241], v[6:9]
	v_mfma_f32_16x16x32_bf16 v[2:5], v[184:187], v[238:241], v[2:5]
	s_barrier
	s_add_i32 vcc_hi, vcc_hi, 2
	s_add_u32 s16, s16, 0x100
	s_addc_u32 s17, s17, 0
	s_add_u32 s78, s78, 0x100
	s_addc_u32 vcc_lo, vcc_lo, 0
	s_cmp_gt_u32 vcc_hi, 29
	s_cbranch_scc0 .LBB0_553
	s_and_b64 vcc, exec, s[6:7]
	s_cbranch_vccz .LBB0_556
	s_barrier

; #define PG8_STAGE(bufoff, gbase, voff) do { _Pragma("unroll") for (int _i = 0; _i < 2; ++_i) \
;         __builtin_amdgcn_global_load_lds((const unsigned*)((const char*)(gbase) + (voff)[_i]), (PG8_LAS unsigned*)(lds + (bufoff) + ldsw + _i * 8192), 16, 0, 0); } while (0)
; #define PG8_LDA(dst, b, h) do { _Pragma("unroll") for (int m = 0; m < 4; ++m) _Pragma("unroll") for (int k = 0; k < 2; ++k) dst[m][k] = *(const PG8_LAS bf16x8*)(lds + PG8_SA(b, h) + aoff + m * 2048 + k * 1024); } while (0)
; #define PG8_LDB(dst, b, h) do { _Pragma("unroll") for (int n = 0; n < 2; ++n) _Pragma("unroll") for (int k = 0; k < 2; ++k) dst[n][k] = *(const PG8_LAS bf16x8*)(lds + PG8_SB(b, h) + boff + n * 2048 + k * 1024); } while (0)
; #define PG8_MMA(ai, bj, At, Bt) do { __builtin_amdgcn_s_setprio(1); _Pragma("unroll") for (int m = 0; m < 4; ++m) _Pragma("unroll") for (int n = 0; n < 2; ++n) _Pragma("unroll") for (int k = 0; k < 2; ++k) \
;         acc[ai][bj][m][n] = __builtin_amdgcn_mfma_f32_16x16x32_bf16(Bt[n][k], At[m][k], acc[ai][bj][m][n], 0, 0, 0); __builtin_amdgcn_s_setprio(0); } while (0)
; #define PG8_WAIT_V(n) asm volatile("s_waitcnt vmcnt(" #n ")" ::: "memory")
; #define PG8_WAIT_L(n) asm volatile("s_waitcnt lgkmcnt(" #n ")" ::: "memory")
; template <class Epi, class Sched, bool ALIGN_EPI = false, bool SP2 = false>
; __device__ __forceinline__ void gemm_phase(PG8_LAS unsigned char* lds, const Gemm g, const Sched& S, const Epi& E) {
;     ...
;             const bool last = (t == nt - 2);
;             const char* a1 = cA + (size_t)(t + 1) * kstep;
;             const char* a2 = last ? nA : cA + (size_t)(t + 2) * kstep; const char* b2 = last ? nB : cB + (size_t)(t + 2) * kstep;
;             const char* a3 = a2 + kstep; const char* b3 = b2 + kstep;
;             if (last && has_next) S.a_ready(nxt);
;             if constexpr (SP2) {
;             PG8_LDB(B0, 0, 0); PG8_LDB(B1, 0, 1); PG8_SCHED; PG8_LDA(At, 0, 0); PG8_STAGE(PG8_SA(1, 1), a1 + hstep, voffA);
;             PG8_WAIT_V(8); PG8_WAIT_L(0); PG8_BAR; PG8_MMA(0, 0, At, B0); PG8_MMA(0, 1, At, B1); PG8_BAR; PG8_SCHED;
;             PG8_LDA(At, 0, 1); PG8_STAGE(PG8_SB(0, 0), b2, voffB); PG8_STAGE(PG8_SB(0, 1), b2 + hstep, voffB); PG8_STAGE(PG8_SA(0, 0), a2, voffA);
;             PG8_WAIT_V(8); PG8_WAIT_L(0); PG8_BAR; PG8_MMA(1, 0, At, B0); PG8_MMA(1, 1, At, B1); PG8_BAR; PG8_SCHED;
.LBB0_659:
	s_add_u32 s26, s16, 0xfff80080
	s_addc_u32 s27, s17, -1
	s_add_i32 s54, 0, 0x10000
	s_cmp_eq_u32 s77, 28
	s_cselect_b32 s29, s23, s27
	s_cselect_b32 s28, s43, s26
	s_cselect_b32 s27, s21, s73
	s_cselect_b32 s26, s52, s53
	s_add_i32 s78, 0, 0x14000
	v_add_u32_e32 v154, s54, v159
	v_add_u32_e32 v163, s78, v159
	ds_read_b128 v[142:145], v154
	ds_read_b128 v[146:149], v154 offset:1024
	ds_read_b128 v[150:153], v154 offset:2048
	ds_read_b128 v[154:157], v154 offset:3072
	ds_read_b128 v[164:167], v163
	ds_read_b128 v[180:183], v163 offset:1024
	ds_read_b128 v[184:187], v163 offset:2048
	ds_read_b128 v[188:191], v163 offset:3072
	v_lshl_add_u64 v[238:239], s[16:17], 0, v[138:139]
	s_add_i32 m0, s45, 0xc000
	ds_read_b128 v[192:195], v162
	ds_read_b128 v[196:199], v162 offset:1024
	ds_read_b128 v[200:203], v162 offset:2048
	ds_read_b128 v[218:221], v162 offset:3072
	ds_read_b128 v[222:225], v162 offset:4096
	ds_read_b128 v[226:229], v162 offset:5120
	ds_read_b128 v[230:233], v162 offset:6144
	ds_read_b128 v[234:237], v162 offset:7168
	global_load_lds_dwordx4 v[238:239], off
	v_lshl_add_u64 v[238:239], s[16:17], 0, v[140:141]
	s_add_i32 m0, s45, 0xe000
	s_nop 0
	global_load_lds_dwordx4 v[238:239], off
	s_waitcnt vmcnt(8)
	s_waitcnt lgkmcnt(0)
	s_barrier
	v_mfma_f32_16x16x32_bf16 v[126:129], v[142:145], v[192:195], v[126:129]
	v_mfma_f32_16x16x32_bf16 v[118:121], v[150:153], v[192:195], v[118:121]
	v_mfma_f32_16x16x32_bf16 v[110:113], v[142:145], v[200:203], v[110:113]
	v_mfma_f32_16x16x32_bf16 v[102:105], v[150:153], v[200:203], v[102:105]
	v_mfma_f32_16x16x32_bf16 v[94:97], v[142:145], v[222:225], v[94:97]
	v_mfma_f32_16x16x32_bf16 v[86:89], v[150:153], v[222:225], v[86:89]
	v_mfma_f32_16x16x32_bf16 v[78:81], v[142:145], v[230:233], v[78:81]
	v_mfma_f32_16x16x32_bf16 v[70:73], v[150:153], v[230:233], v[70:73]
	v_mfma_f32_16x16x32_bf16 v[126:129], v[146:149], v[196:199], v[126:129]
	v_mfma_f32_16x16x32_bf16 v[118:121], v[154:157], v[196:199], v[118:121]
	v_mfma_f32_16x16x32_bf16 v[110:113], v[146:149], v[218:221], v[110:113]
	v_mfma_f32_16x16x32_bf16 v[102:105], v[154:157], v[218:221], v[102:105]
	v_mfma_f32_16x16x32_bf16 v[94:97], v[146:149], v[226:229], v[94:97]
	v_mfma_f32_16x16x32_bf16 v[86:89], v[154:157], v[226:229], v[86:89]
	v_mfma_f32_16x16x32_bf16 v[78:81], v[146:149], v[234:237], v[78:81]
	v_mfma_f32_16x16x32_bf16 v[70:73], v[154:157], v[234:237], v[70:73]
	v_mfma_f32_16x16x32_bf16 v[122:125], v[164:167], v[192:195], v[122:125]
	v_mfma_f32_16x16x32_bf16 v[114:117], v[184:187], v[192:195], v[114:117]
	v_mfma_f32_16x16x32_bf16 v[106:109], v[164:167], v[200:203], v[106:109]
	v_mfma_f32_16x16x32_bf16 v[98:101], v[184:187], v[200:203], v[98:101]
	v_mfma_f32_16x16x32_bf16 v[90:93], v[164:167], v[222:225], v[90:93]
	v_mfma_f32_16x16x32_bf16 v[82:85], v[184:187], v[222:225], v[82:85]
	v_mfma_f32_16x16x32_bf16 v[74:77], v[164:167], v[230:233], v[74:77]
	v_mfma_f32_16x16x32_bf16 v[66:69], v[184:187], v[230:233], v[66:69]
	v_mfma_f32_16x16x32_bf16 v[122:125], v[180:183], v[196:199], v[122:125]
	v_mfma_f32_16x16x32_bf16 v[114:117], v[188:191], v[196:199], v[114:117]
	v_mfma_f32_16x16x32_bf16 v[106:109], v[180:183], v[218:221], v[106:109]
	v_mfma_f32_16x16x32_bf16 v[98:101], v[188:191], v[218:221], v[98:101]
	v_mfma_f32_16x16x32_bf16 v[90:93], v[180:183], v[226:229], v[90:93]
	v_mfma_f32_16x16x32_bf16 v[82:85], v[188:191], v[226:229], v[82:85]
	v_mfma_f32_16x16x32_bf16 v[74:77], v[180:183], v[234:237], v[74:77]
	v_mfma_f32_16x16x32_bf16 v[66:69], v[188:191], v[234:237], v[66:69]
	s_barrier
	s_add_i32 s54, s54, s38
	v_lshl_add_u64 v[238:239], s[26:27], 0, v[0:1]
	s_mov_b32 m0, s54
	ds_read_b128 v[192:195], v162 offset:16384
	ds_read_b128 v[196:199], v162 offset:17408
	ds_read_b128 v[200:203], v162 offset:18432
	ds_read_b128 v[218:221], v162 offset:19456
	ds_read_b128 v[222:225], v162 offset:20480
	ds_read_b128 v[226:229], v162 offset:21504
	ds_read_b128 v[230:233], v162 offset:22528
	ds_read_b128 v[234:237], v162 offset:23552
	global_load_lds_dwordx4 v[238:239], off
	s_add_i32 m0, s54, 0x2000
	s_add_u32 s54, s26, 0x80000
	v_lshl_add_u64 v[240:241], s[26:27], 0, v[130:131]
	s_addc_u32 s55, s27, 0
	s_add_i32 s78, s78, s38
	global_load_lds_dwordx4 v[240:241], off
	v_lshl_add_u64 v[242:243], s[54:55], 0, v[0:1]
	s_mov_b32 m0, s78
	v_lshl_add_u64 v[244:245], s[28:29], 0, v[132:133]
	global_load_lds_dwordx4 v[242:243], off
	v_lshl_add_u64 v[242:243], s[54:55], 0, v[130:131]
	s_add_i32 m0, s78, 0x2000
	s_nop 0
	global_load_lds_dwordx4 v[242:243], off
	v_lshl_add_u64 v[242:243], s[28:29], 0, v[134:135]
	s_mov_b32 m0, s45
	s_nop 0
	global_load_lds_dwordx4 v[242:243], off
	s_mov_b32 m0, s46
	s_nop 0
	global_load_lds_dwordx4 v[244:245], off
	s_waitcnt vmcnt(8)
	s_waitcnt lgkmcnt(0)
	s_barrier
; #define PG8_STAGE(bufoff, gbase, voff) do { _Pragma("unroll") for (int _i = 0; _i < 2; ++_i) \
;         __builtin_amdgcn_global_load_lds((const unsigned*)((const char*)(gbase) + (voff)[_i]), (PG8_LAS unsigned*)(lds + (bufoff) + ldsw + _i * 8192), 16, 0, 0); } while (0)
; #define PG8_LDA(dst, b, h) do { _Pragma("unroll") for (int m = 0; m < 4; ++m) _Pragma("unroll") for (int k = 0; k < 2; ++k) dst[m][k] = *(const PG8_LAS bf16x8*)(lds + PG8_SA(b, h) + aoff + m * 2048 + k * 1024); } while (0)
; #define PG8_LDB(dst, b, h) do { _Pragma("unroll") for (int n = 0; n < 2; ++n) _Pragma("unroll") for (int k = 0; k < 2; ++k) dst[n][k] = *(const PG8_LAS bf16x8*)(lds + PG8_SB(b, h) + boff + n * 2048 + k * 1024); } while (0)
; #define PG8_MMA(ai, bj, At, Bt) do { __builtin_amdgcn_s_setprio(1); _Pragma("unroll") for (int m = 0; m < 4; ++m) _Pragma("unroll") for (int n = 0; n < 2; ++n) _Pragma("unroll") for (int k = 0; k < 2; ++k) \
;         acc[ai][bj][m][n] = __builtin_amdgcn_mfma_f32_16x16x32_bf16(Bt[n][k], At[m][k], acc[ai][bj][m][n], 0, 0, 0); __builtin_amdgcn_s_setprio(0); } while (0)
; #define PG8_WAIT_V(n) asm volatile("s_waitcnt vmcnt(" #n ")" ::: "memory")
; #define PG8_WAIT_L(n) asm volatile("s_waitcnt lgkmcnt(" #n ")" ::: "memory")
; #define PG8_BAR __builtin_amdgcn_s_barrier()
; #define PG8_SCHED __builtin_amdgcn_sched_barrier(0)
; template <class Epi, class Sched, bool ALIGN_EPI = false, bool SP2 = false>
; __device__ __forceinline__ void gemm_phase(PG8_LAS unsigned char* lds, const Gemm g, const Sched& S, const Epi& E) {
;     ...
;             PG8_WAIT_V(8); PG8_WAIT_L(0); PG8_BAR; PG8_MMA(1, 0, At, B0); PG8_MMA(1, 1, At, B1); PG8_BAR; PG8_SCHED;
;             PG8_LDB(B0, 1, 0); PG8_LDB(B1, 1, 1); PG8_SCHED; PG8_LDA(At, 1, 0); PG8_STAGE(PG8_SA(0, 1), a2 + hstep, voffA);
;             PG8_WAIT_V(8); PG8_WAIT_L(0); PG8_BAR; PG8_MMA(0, 0, At, B0); PG8_MMA(0, 1, At, B1); PG8_BAR; PG8_SCHED;
	v_mfma_f32_16x16x32_bf16 v[62:65], v[142:145], v[192:195], v[62:65]
	v_mfma_f32_16x16x32_bf16 v[54:57], v[150:153], v[192:195], v[54:57]
	v_mfma_f32_16x16x32_bf16 v[46:49], v[142:145], v[200:203], v[46:49]
	v_mfma_f32_16x16x32_bf16 v[38:41], v[150:153], v[200:203], v[38:41]
	v_mfma_f32_16x16x32_bf16 v[30:33], v[142:145], v[222:225], v[30:33]
	v_mfma_f32_16x16x32_bf16 v[22:25], v[150:153], v[222:225], v[22:25]
	v_mfma_f32_16x16x32_bf16 v[14:17], v[142:145], v[230:233], v[14:17]
	v_mfma_f32_16x16x32_bf16 v[6:9], v[150:153], v[230:233], v[6:9]
	v_mfma_f32_16x16x32_bf16 v[62:65], v[146:149], v[196:199], v[62:65]
	v_mfma_f32_16x16x32_bf16 v[54:57], v[154:157], v[196:199], v[54:57]
	v_mfma_f32_16x16x32_bf16 v[46:49], v[146:149], v[218:221], v[46:49]
	v_mfma_f32_16x16x32_bf16 v[38:41], v[154:157], v[218:221], v[38:41]
	v_mfma_f32_16x16x32_bf16 v[30:33], v[146:149], v[226:229], v[30:33]
	v_mfma_f32_16x16x32_bf16 v[22:25], v[154:157], v[226:229], v[22:25]
	v_mfma_f32_16x16x32_bf16 v[14:17], v[146:149], v[234:237], v[14:17]
	v_mfma_f32_16x16x32_bf16 v[6:9], v[154:157], v[234:237], v[6:9]
	v_mfma_f32_16x16x32_bf16 v[58:61], v[164:167], v[192:195], v[58:61]
	v_mfma_f32_16x16x32_bf16 v[50:53], v[184:187], v[192:195], v[50:53]
	v_mfma_f32_16x16x32_bf16 v[42:45], v[164:167], v[200:203], v[42:45]
	v_mfma_f32_16x16x32_bf16 v[34:37], v[184:187], v[200:203], v[34:37]
	v_mfma_f32_16x16x32_bf16 v[26:29], v[164:167], v[222:225], v[26:29]
	v_mfma_f32_16x16x32_bf16 v[18:21], v[184:187], v[222:225], v[18:21]
	v_mfma_f32_16x16x32_bf16 v[10:13], v[164:167], v[230:233], v[10:13]
	v_mfma_f32_16x16x32_bf16 v[2:5], v[184:187], v[230:233], v[2:5]
	v_mfma_f32_16x16x32_bf16 v[58:61], v[180:183], v[196:199], v[58:61]
	v_mfma_f32_16x16x32_bf16 v[50:53], v[188:191], v[196:199], v[50:53]
	v_mfma_f32_16x16x32_bf16 v[42:45], v[180:183], v[218:221], v[42:45]
	v_mfma_f32_16x16x32_bf16 v[34:37], v[188:191], v[218:221], v[34:37]
	v_mfma_f32_16x16x32_bf16 v[26:29], v[180:183], v[226:229], v[26:29]
	v_mfma_f32_16x16x32_bf16 v[18:21], v[188:191], v[226:229], v[18:21]
	v_mfma_f32_16x16x32_bf16 v[10:13], v[180:183], v[234:237], v[10:13]
	v_mfma_f32_16x16x32_bf16 v[2:5], v[188:191], v[234:237], v[2:5]
	s_barrier
	s_add_i32 s54, 0, 0x18000
	s_add_i32 s55, 0, 0x1c000
	v_add_u32_e32 v154, s54, v159
	v_add_u32_e32 v163, s55, v159
	ds_read_b128 v[142:145], v154
	ds_read_b128 v[146:149], v154 offset:1024
	ds_read_b128 v[150:153], v154 offset:2048
	ds_read_b128 v[154:157], v154 offset:3072
	ds_read_b128 v[164:167], v163
	ds_read_b128 v[180:183], v163 offset:1024
	ds_read_b128 v[184:187], v163 offset:2048
	ds_read_b128 v[188:191], v163 offset:3072
	s_add_u32 s28, s28, 0x80000
	s_addc_u32 s29, s29, 0
	s_mov_b32 m0, s47
	v_lshl_add_u64 v[246:247], s[28:29], 0, v[134:135]
	ds_read_b128 v[192:195], v162 offset:32768
	ds_read_b128 v[196:199], v162 offset:33792
	ds_read_b128 v[200:203], v162 offset:34816
	ds_read_b128 v[218:221], v162 offset:35840
	ds_read_b128 v[222:225], v162 offset:36864
	ds_read_b128 v[226:229], v162 offset:37888
	ds_read_b128 v[230:233], v162 offset:38912
	ds_read_b128 v[234:237], v162 offset:39936
	global_load_lds_dwordx4 v[246:247], off
	v_lshl_add_u64 v[246:247], s[28:29], 0, v[132:133]
	s_mov_b32 m0, s48
	s_nop 0
	global_load_lds_dwordx4 v[246:247], off
	s_waitcnt vmcnt(8)
	s_waitcnt lgkmcnt(0)
	s_barrier
	v_mfma_f32_16x16x32_bf16 v[126:129], v[142:145], v[192:195], v[126:129]
	v_mfma_f32_16x16x32_bf16 v[118:121], v[150:153], v[192:195], v[118:121]
	v_mfma_f32_16x16x32_bf16 v[110:113], v[142:145], v[200:203], v[110:113]
	v_mfma_f32_16x16x32_bf16 v[102:105], v[150:153], v[200:203], v[102:105]
	v_mfma_f32_16x16x32_bf16 v[94:97], v[142:145], v[222:225], v[94:97]
	v_mfma_f32_16x16x32_bf16 v[86:89], v[150:153], v[222:225], v[86:89]
	v_mfma_f32_16x16x32_bf16 v[78:81], v[142:145], v[230:233], v[78:81]
	v_mfma_f32_16x16x32_bf16 v[70:73], v[150:153], v[230:233], v[70:73]
	v_mfma_f32_16x16x32_bf16 v[126:129], v[146:149], v[196:199], v[126:129]
	v_mfma_f32_16x16x32_bf16 v[118:121], v[154:157], v[196:199], v[118:121]
	v_mfma_f32_16x16x32_bf16 v[110:113], v[146:149], v[218:221], v[110:113]
	v_mfma_f32_16x16x32_bf16 v[102:105], v[154:157], v[218:221], v[102:105]
	v_mfma_f32_16x16x32_bf16 v[94:97], v[146:149], v[226:229], v[94:97]
	v_mfma_f32_16x16x32_bf16 v[86:89], v[154:157], v[226:229], v[86:89]
	v_mfma_f32_16x16x32_bf16 v[78:81], v[146:149], v[234:237], v[78:81]
	v_mfma_f32_16x16x32_bf16 v[70:73], v[154:157], v[234:237], v[70:73]
	v_mfma_f32_16x16x32_bf16 v[122:125], v[164:167], v[192:195], v[122:125]
	v_mfma_f32_16x16x32_bf16 v[114:117], v[184:187], v[192:195], v[114:117]
	v_mfma_f32_16x16x32_bf16 v[106:109], v[164:167], v[200:203], v[106:109]
	v_mfma_f32_16x16x32_bf16 v[98:101], v[184:187], v[200:203], v[98:101]
	v_mfma_f32_16x16x32_bf16 v[90:93], v[164:167], v[222:225], v[90:93]
	v_mfma_f32_16x16x32_bf16 v[82:85], v[184:187], v[222:225], v[82:85]
	v_mfma_f32_16x16x32_bf16 v[74:77], v[164:167], v[230:233], v[74:77]
	v_mfma_f32_16x16x32_bf16 v[66:69], v[184:187], v[230:233], v[66:69]
	v_mfma_f32_16x16x32_bf16 v[122:125], v[180:183], v[196:199], v[122:125]
	v_mfma_f32_16x16x32_bf16 v[114:117], v[188:191], v[196:199], v[114:117]
	v_mfma_f32_16x16x32_bf16 v[106:109], v[180:183], v[218:221], v[106:109]
	v_mfma_f32_16x16x32_bf16 v[98:101], v[188:191], v[218:221], v[98:101]
	v_mfma_f32_16x16x32_bf16 v[90:93], v[180:183], v[226:229], v[90:93]
	v_mfma_f32_16x16x32_bf16 v[82:85], v[188:191], v[226:229], v[82:85]
	v_mfma_f32_16x16x32_bf16 v[74:77], v[180:183], v[234:237], v[74:77]
	v_mfma_f32_16x16x32_bf16 v[66:69], v[188:191], v[234:237], v[66:69]
	s_barrier
; #define PG8_STAGE(bufoff, gbase, voff) do { _Pragma("unroll") for (int _i = 0; _i < 2; ++_i) \
;         __builtin_amdgcn_global_load_lds((const unsigned*)((const char*)(gbase) + (voff)[_i]), (PG8_LAS unsigned*)(lds + (bufoff) + ldsw + _i * 8192), 16, 0, 0); } while (0)
; #define PG8_LDA(dst, b, h) do { _Pragma("unroll") for (int m = 0; m < 4; ++m) _Pragma("unroll") for (int k = 0; k < 2; ++k) dst[m][k] = *(const PG8_LAS bf16x8*)(lds + PG8_SA(b, h) + aoff + m * 2048 + k * 1024); } while (0)
; #define PG8_MMA(ai, bj, At, Bt) do { __builtin_amdgcn_s_setprio(1); _Pragma("unroll") for (int m = 0; m < 4; ++m) _Pragma("unroll") for (int n = 0; n < 2; ++n) _Pragma("unroll") for (int k = 0; k < 2; ++k) \
;         acc[ai][bj][m][n] = __builtin_amdgcn_mfma_f32_16x16x32_bf16(Bt[n][k], At[m][k], acc[ai][bj][m][n], 0, 0, 0); __builtin_amdgcn_s_setprio(0); } while (0)
; #define PG8_WAIT_V(n) asm volatile("s_waitcnt vmcnt(" #n ")" ::: "memory")
; #define PG8_WAIT_L(n) asm volatile("s_waitcnt lgkmcnt(" #n ")" ::: "memory")
; #define PG8_BAR __builtin_amdgcn_s_barrier()
; #define PG8_SCHED __builtin_amdgcn_sched_barrier(0)
; template <class Epi, class Sched, bool ALIGN_EPI = false, bool SP2 = false>
; __device__ __forceinline__ void gemm_phase(PG8_LAS unsigned char* lds, const Gemm g, const Sched& S, const Epi& E) {
;     ...
;         for (int t = 0; t < nt; t += 2) {
;     ...
;             PG8_LDA(At, 1, 1); PG8_STAGE(PG8_SB(1, 0), b3, voffB); PG8_STAGE(PG8_SB(1, 1), b3 + hstep, voffB); PG8_STAGE(PG8_SA(1, 0), a3, voffA);
;             PG8_WAIT_V(8); PG8_WAIT_L(0); PG8_BAR; PG8_MMA(1, 0, At, B0); PG8_MMA(1, 1, At, B1); PG8_BAR; PG8_SCHED;
	s_add_i32 s28, s54, s38
	v_lshl_add_u64 v[238:239], v[238:239], 0, s[34:35]
	s_mov_b32 m0, s28
	ds_read_b128 v[192:195], v162 offset:49152
	ds_read_b128 v[196:199], v162 offset:50176
	ds_read_b128 v[200:203], v162 offset:51200
	ds_read_b128 v[218:221], v162 offset:52224
	ds_read_b128 v[222:225], v162 offset:53248
	ds_read_b128 v[226:229], v162 offset:54272
	ds_read_b128 v[230:233], v162 offset:55296
	ds_read_b128 v[234:237], v162 offset:56320
	global_load_lds_dwordx4 v[238:239], off
	s_add_i32 m0, s28, 0x2000
	s_add_u32 s26, s26, 0x80080
	v_lshl_add_u64 v[238:239], v[240:241], 0, s[34:35]
	s_addc_u32 s27, s27, 0
	s_add_i32 s28, s55, s38
	global_load_lds_dwordx4 v[238:239], off
	v_lshl_add_u64 v[238:239], s[26:27], 0, v[0:1]
	s_mov_b32 m0, s28
	s_nop 0
	global_load_lds_dwordx4 v[238:239], off
	v_lshl_add_u64 v[238:239], s[26:27], 0, v[130:131]
	s_add_i32 m0, s28, 0x2000
	s_nop 0
	global_load_lds_dwordx4 v[238:239], off
	v_lshl_add_u64 v[238:239], v[242:243], 0, s[34:35]
	s_mov_b32 m0, s4
	s_nop 0
	global_load_lds_dwordx4 v[238:239], off
	v_lshl_add_u64 v[238:239], v[244:245], 0, s[34:35]
	s_mov_b32 m0, s49
	s_nop 0
	global_load_lds_dwordx4 v[238:239], off
	s_waitcnt vmcnt(8)
	s_waitcnt lgkmcnt(0)
	s_barrier
	v_mfma_f32_16x16x32_bf16 v[62:65], v[142:145], v[192:195], v[62:65]
	v_mfma_f32_16x16x32_bf16 v[54:57], v[150:153], v[192:195], v[54:57]
	v_mfma_f32_16x16x32_bf16 v[46:49], v[142:145], v[200:203], v[46:49]
	v_mfma_f32_16x16x32_bf16 v[38:41], v[150:153], v[200:203], v[38:41]
	v_mfma_f32_16x16x32_bf16 v[30:33], v[142:145], v[222:225], v[30:33]
	v_mfma_f32_16x16x32_bf16 v[22:25], v[150:153], v[222:225], v[22:25]
	v_mfma_f32_16x16x32_bf16 v[14:17], v[142:145], v[230:233], v[14:17]
	v_mfma_f32_16x16x32_bf16 v[6:9], v[150:153], v[230:233], v[6:9]
	v_mfma_f32_16x16x32_bf16 v[62:65], v[146:149], v[196:199], v[62:65]
	v_mfma_f32_16x16x32_bf16 v[54:57], v[154:157], v[196:199], v[54:57]
	v_mfma_f32_16x16x32_bf16 v[46:49], v[146:149], v[218:221], v[46:49]
	v_mfma_f32_16x16x32_bf16 v[38:41], v[154:157], v[218:221], v[38:41]
	v_mfma_f32_16x16x32_bf16 v[30:33], v[146:149], v[226:229], v[30:33]
	v_mfma_f32_16x16x32_bf16 v[22:25], v[154:157], v[226:229], v[22:25]
	v_mfma_f32_16x16x32_bf16 v[14:17], v[146:149], v[234:237], v[14:17]
	v_mfma_f32_16x16x32_bf16 v[6:9], v[154:157], v[234:237], v[6:9]
	v_mfma_f32_16x16x32_bf16 v[58:61], v[164:167], v[192:195], v[58:61]
	v_mfma_f32_16x16x32_bf16 v[50:53], v[184:187], v[192:195], v[50:53]
	v_mfma_f32_16x16x32_bf16 v[42:45], v[164:167], v[200:203], v[42:45]
	v_mfma_f32_16x16x32_bf16 v[34:37], v[184:187], v[200:203], v[34:37]
	v_mfma_f32_16x16x32_bf16 v[26:29], v[164:167], v[222:225], v[26:29]
	v_mfma_f32_16x16x32_bf16 v[18:21], v[184:187], v[222:225], v[18:21]
	v_mfma_f32_16x16x32_bf16 v[10:13], v[164:167], v[230:233], v[10:13]
	v_mfma_f32_16x16x32_bf16 v[2:5], v[184:187], v[230:233], v[2:5]
	v_mfma_f32_16x16x32_bf16 v[58:61], v[180:183], v[196:199], v[58:61]
	v_mfma_f32_16x16x32_bf16 v[50:53], v[188:191], v[196:199], v[50:53]
	v_mfma_f32_16x16x32_bf16 v[42:45], v[180:183], v[218:221], v[42:45]
	v_mfma_f32_16x16x32_bf16 v[34:37], v[188:191], v[218:221], v[34:37]
	v_mfma_f32_16x16x32_bf16 v[26:29], v[180:183], v[226:229], v[26:29]
	v_mfma_f32_16x16x32_bf16 v[18:21], v[188:191], v[226:229], v[18:21]
	v_mfma_f32_16x16x32_bf16 v[10:13], v[180:183], v[234:237], v[10:13]
	v_mfma_f32_16x16x32_bf16 v[2:5], v[188:191], v[234:237], v[2:5]
	s_barrier
	s_add_i32 s77, s77, 2
	s_add_u32 s16, s16, 0x100
	s_addc_u32 s17, s17, 0
	s_add_u32 s53, s53, 0x100
	s_addc_u32 s73, s73, 0
	s_cmp_gt_u32 s77, 29
	s_cbranch_scc0 .LBB0_659
	s_and_b64 vcc, exec, s[18:19]
	s_cbranch_vccz .LBB0_662
	s_barrier

; #define PG8_STAGE(bufoff, gbase, voff) do { _Pragma("unroll") for (int _i = 0; _i < 2; ++_i) \
;         __builtin_amdgcn_global_load_lds((const unsigned*)((const char*)(gbase) + (voff)[_i]), (PG8_LAS unsigned*)(lds + (bufoff) + ldsw + _i * 8192), 16, 0, 0); } while (0)
; #define PG8_LDA(dst, b, h) do { _Pragma("unroll") for (int m = 0; m < 4; ++m) _Pragma("unroll") for (int k = 0; k < 2; ++k) dst[m][k] = *(const PG8_LAS bf16x8*)(lds + PG8_SA(b, h) + aoff + m * 2048 + k * 1024); } while (0)
; #define PG8_LDB(dst, b, h) do { _Pragma("unroll") for (int n = 0; n < 2; ++n) _Pragma("unroll") for (int k = 0; k < 2; ++k) dst[n][k] = *(const PG8_LAS bf16x8*)(lds + PG8_SB(b, h) + boff + n * 2048 + k * 1024); } while (0)
; #define PG8_MMA(ai, bj, At, Bt) do { __builtin_amdgcn_s_setprio(1); _Pragma("unroll") for (int m = 0; m < 4; ++m) _Pragma("unroll") for (int n = 0; n < 2; ++n) _Pragma("unroll") for (int k = 0; k < 2; ++k) \
;         acc[ai][bj][m][n] = __builtin_amdgcn_mfma_f32_16x16x32_bf16(Bt[n][k], At[m][k], acc[ai][bj][m][n], 0, 0, 0); __builtin_amdgcn_s_setprio(0); } while (0)
; #define PG8_WAIT_V(n) asm volatile("s_waitcnt vmcnt(" #n ")" ::: "memory")
; #define PG8_WAIT_L(n) asm volatile("s_waitcnt lgkmcnt(" #n ")" ::: "memory")
; template <class Epi, class Sched, bool ALIGN_EPI = false, bool SP2 = false>
; __device__ __forceinline__ void gemm_phase(PG8_LAS unsigned char* lds, const Gemm g, const Sched& S, const Epi& E) {
;     ...
;             const bool last = (t == nt - 2);
;             const char* a1 = cA + (size_t)(t + 1) * kstep;
;             const char* a2 = last ? nA : cA + (size_t)(t + 2) * kstep; const char* b2 = last ? nB : cB + (size_t)(t + 2) * kstep;
;             const char* a3 = a2 + kstep; const char* b3 = b2 + kstep;
;             if (last && has_next) S.a_ready(nxt);
;             if constexpr (SP2) {
;             PG8_LDB(B0, 0, 0); PG8_LDB(B1, 0, 1); PG8_SCHED; PG8_LDA(At, 0, 0); PG8_STAGE(PG8_SA(1, 1), a1 + hstep, voffA);
;             PG8_WAIT_V(8); PG8_WAIT_L(0); PG8_BAR; PG8_MMA(0, 0, At, B0); PG8_MMA(0, 1, At, B1); PG8_BAR; PG8_SCHED;
;             PG8_LDA(At, 0, 1); PG8_STAGE(PG8_SB(0, 0), b2, voffB); PG8_STAGE(PG8_SB(0, 1), b2 + hstep, voffB); PG8_STAGE(PG8_SA(0, 0), a2, voffA);
;             PG8_WAIT_V(8); PG8_WAIT_L(0); PG8_BAR; PG8_MMA(1, 0, At, B0); PG8_MMA(1, 1, At, B1); PG8_BAR; PG8_SCHED;
.LBB0_802:
	s_add_u32 s24, s22, 0x100
	s_addc_u32 s25, s23, 0
	s_add_i32 s54, 0, 0x10000
	s_cmpk_eq_i32 s78, 0x54
	s_cselect_b32 s29, s19, s25
	s_cselect_b32 s28, s18, s24
	s_cselect_b32 s27, s21, s45
	s_cselect_b32 s26, s20, s44
	s_add_i32 s55, 0, 0x14000
	v_add_u32_e32 v142, s54, v199
	v_add_u32_e32 v182, s55, v199
	ds_read_b128 v[122:125], v142
	ds_read_b128 v[134:137], v142 offset:1024
	ds_read_b128 v[138:141], v142 offset:2048
	ds_read_b128 v[142:145], v142 offset:3072
	ds_read_b128 v[146:149], v182
	ds_read_b128 v[150:153], v182 offset:1024
	ds_read_b128 v[154:157], v182 offset:2048
	ds_read_b128 v[182:185], v182 offset:3072
	v_lshl_add_u64 v[238:239], s[22:23], 0, v[166:167]
	s_add_i32 m0, s46, 0xc000
	ds_read_b128 v[186:189], v202
	ds_read_b128 v[190:193], v202 offset:1024
	ds_read_b128 v[194:197], v202 offset:2048
	ds_read_b128 v[218:221], v202 offset:3072
	ds_read_b128 v[222:225], v202 offset:4096
	ds_read_b128 v[226:229], v202 offset:5120
	ds_read_b128 v[230:233], v202 offset:6144
	ds_read_b128 v[234:237], v202 offset:7168
	global_load_lds_dwordx4 v[238:239], off
	v_lshl_add_u64 v[238:239], s[22:23], 0, v[180:181]
	s_add_i32 m0, s46, 0xe000
	s_nop 0
	global_load_lds_dwordx4 v[238:239], off
	s_waitcnt vmcnt(8)
	s_waitcnt lgkmcnt(0)
	s_barrier
	v_mfma_f32_16x16x32_bf16 v[130:133], v[122:125], v[186:189], v[130:133]
	v_mfma_f32_16x16x32_bf16 v[126:129], v[138:141], v[186:189], v[126:129]
	v_mfma_f32_16x16x32_bf16 v[110:113], v[122:125], v[194:197], v[110:113]
	v_mfma_f32_16x16x32_bf16 v[106:109], v[138:141], v[194:197], v[106:109]
	v_mfma_f32_16x16x32_bf16 v[94:97], v[122:125], v[222:225], v[94:97]
	v_mfma_f32_16x16x32_bf16 v[90:93], v[138:141], v[222:225], v[90:93]
	v_mfma_f32_16x16x32_bf16 v[78:81], v[122:125], v[230:233], v[78:81]
	v_mfma_f32_16x16x32_bf16 v[74:77], v[138:141], v[230:233], v[74:77]
	v_mfma_f32_16x16x32_bf16 v[130:133], v[134:137], v[190:193], v[130:133]
	v_mfma_f32_16x16x32_bf16 v[126:129], v[142:145], v[190:193], v[126:129]
	v_mfma_f32_16x16x32_bf16 v[110:113], v[134:137], v[218:221], v[110:113]
	v_mfma_f32_16x16x32_bf16 v[106:109], v[142:145], v[218:221], v[106:109]
	v_mfma_f32_16x16x32_bf16 v[94:97], v[134:137], v[226:229], v[94:97]
	v_mfma_f32_16x16x32_bf16 v[90:93], v[142:145], v[226:229], v[90:93]
	v_mfma_f32_16x16x32_bf16 v[78:81], v[134:137], v[234:237], v[78:81]
	v_mfma_f32_16x16x32_bf16 v[74:77], v[142:145], v[234:237], v[74:77]
	v_mfma_f32_16x16x32_bf16 v[118:121], v[146:149], v[186:189], v[118:121]
	v_mfma_f32_16x16x32_bf16 v[114:117], v[154:157], v[186:189], v[114:117]
	v_mfma_f32_16x16x32_bf16 v[102:105], v[146:149], v[194:197], v[102:105]
	v_mfma_f32_16x16x32_bf16 v[98:101], v[154:157], v[194:197], v[98:101]
	v_mfma_f32_16x16x32_bf16 v[86:89], v[146:149], v[222:225], v[86:89]
	v_mfma_f32_16x16x32_bf16 v[82:85], v[154:157], v[222:225], v[82:85]
	v_mfma_f32_16x16x32_bf16 v[70:73], v[146:149], v[230:233], v[70:73]
	v_mfma_f32_16x16x32_bf16 v[66:69], v[154:157], v[230:233], v[66:69]
	v_mfma_f32_16x16x32_bf16 v[118:121], v[150:153], v[190:193], v[118:121]
	v_mfma_f32_16x16x32_bf16 v[114:117], v[182:185], v[190:193], v[114:117]
	v_mfma_f32_16x16x32_bf16 v[102:105], v[150:153], v[218:221], v[102:105]
	v_mfma_f32_16x16x32_bf16 v[98:101], v[182:185], v[218:221], v[98:101]
	v_mfma_f32_16x16x32_bf16 v[86:89], v[150:153], v[226:229], v[86:89]
	v_mfma_f32_16x16x32_bf16 v[82:85], v[182:185], v[226:229], v[82:85]
	v_mfma_f32_16x16x32_bf16 v[70:73], v[150:153], v[234:237], v[70:73]
	v_mfma_f32_16x16x32_bf16 v[66:69], v[182:185], v[234:237], v[66:69]
	s_barrier
	s_add_i32 s22, s54, s2
	v_lshl_add_u64 v[238:239], s[26:27], 0, v[0:1]
	s_mov_b32 m0, s22
	ds_read_b128 v[186:189], v202 offset:16384
	ds_read_b128 v[190:193], v202 offset:17408
	ds_read_b128 v[194:197], v202 offset:18432
	ds_read_b128 v[218:221], v202 offset:19456
	ds_read_b128 v[222:225], v202 offset:20480
	ds_read_b128 v[226:229], v202 offset:21504
	ds_read_b128 v[230:233], v202 offset:22528
	ds_read_b128 v[234:237], v202 offset:23552
	global_load_lds_dwordx4 v[238:239], off
	s_add_i32 m0, s22, 0x2000
	s_add_u32 s22, s26, 0x160000
	v_lshl_add_u64 v[240:241], s[26:27], 0, v[158:159]
	s_addc_u32 s23, s27, 0
	s_add_i32 s54, s55, s2
	global_load_lds_dwordx4 v[240:241], off
	v_lshl_add_u64 v[242:243], s[22:23], 0, v[0:1]
	s_mov_b32 m0, s54
	v_lshl_add_u64 v[244:245], s[28:29], 0, v[160:161]
	global_load_lds_dwordx4 v[242:243], off
	v_lshl_add_u64 v[242:243], s[22:23], 0, v[158:159]
	s_add_i32 m0, s54, 0x2000
	s_nop 0
	global_load_lds_dwordx4 v[242:243], off
	v_lshl_add_u64 v[242:243], s[28:29], 0, v[162:163]
	s_mov_b32 m0, s46
	s_nop 0
	global_load_lds_dwordx4 v[242:243], off
	s_mov_b32 m0, s47
	s_nop 0
	global_load_lds_dwordx4 v[244:245], off
	s_waitcnt vmcnt(8)
	s_waitcnt lgkmcnt(0)
	s_barrier
; #define PG8_STAGE(bufoff, gbase, voff) do { _Pragma("unroll") for (int _i = 0; _i < 2; ++_i) \
;         __builtin_amdgcn_global_load_lds((const unsigned*)((const char*)(gbase) + (voff)[_i]), (PG8_LAS unsigned*)(lds + (bufoff) + ldsw + _i * 8192), 16, 0, 0); } while (0)
; #define PG8_LDA(dst, b, h) do { _Pragma("unroll") for (int m = 0; m < 4; ++m) _Pragma("unroll") for (int k = 0; k < 2; ++k) dst[m][k] = *(const PG8_LAS bf16x8*)(lds + PG8_SA(b, h) + aoff + m * 2048 + k * 1024); } while (0)
; #define PG8_LDB(dst, b, h) do { _Pragma("unroll") for (int n = 0; n < 2; ++n) _Pragma("unroll") for (int k = 0; k < 2; ++k) dst[n][k] = *(const PG8_LAS bf16x8*)(lds + PG8_SB(b, h) + boff + n * 2048 + k * 1024); } while (0)
; #define PG8_MMA(ai, bj, At, Bt) do { __builtin_amdgcn_s_setprio(1); _Pragma("unroll") for (int m = 0; m < 4; ++m) _Pragma("unroll") for (int n = 0; n < 2; ++n) _Pragma("unroll") for (int k = 0; k < 2; ++k) \
;         acc[ai][bj][m][n] = __builtin_amdgcn_mfma_f32_16x16x32_bf16(Bt[n][k], At[m][k], acc[ai][bj][m][n], 0, 0, 0); __builtin_amdgcn_s_setprio(0); } while (0)
; #define PG8_WAIT_V(n) asm volatile("s_waitcnt vmcnt(" #n ")" ::: "memory")
; #define PG8_WAIT_L(n) asm volatile("s_waitcnt lgkmcnt(" #n ")" ::: "memory")
; #define PG8_BAR __builtin_amdgcn_s_barrier()
; #define PG8_SCHED __builtin_amdgcn_sched_barrier(0)
; template <class Epi, class Sched, bool ALIGN_EPI = false, bool SP2 = false>
; __device__ __forceinline__ void gemm_phase(PG8_LAS unsigned char* lds, const Gemm g, const Sched& S, const Epi& E) {
;     ...
;             PG8_WAIT_V(8); PG8_WAIT_L(0); PG8_BAR; PG8_MMA(1, 0, At, B0); PG8_MMA(1, 1, At, B1); PG8_BAR; PG8_SCHED;
;             PG8_LDB(B0, 1, 0); PG8_LDB(B1, 1, 1); PG8_SCHED; PG8_LDA(At, 1, 0); PG8_STAGE(PG8_SA(0, 1), a2 + hstep, voffA);
;             PG8_WAIT_V(8); PG8_WAIT_L(0); PG8_BAR; PG8_MMA(0, 0, At, B0); PG8_MMA(0, 1, At, B1); PG8_BAR; PG8_SCHED;
	v_mfma_f32_16x16x32_bf16 v[62:65], v[122:125], v[186:189], v[62:65]
	v_mfma_f32_16x16x32_bf16 v[58:61], v[138:141], v[186:189], v[58:61]
	v_mfma_f32_16x16x32_bf16 v[46:49], v[122:125], v[194:197], v[46:49]
	v_mfma_f32_16x16x32_bf16 v[42:45], v[138:141], v[194:197], v[42:45]
	v_mfma_f32_16x16x32_bf16 v[30:33], v[122:125], v[222:225], v[30:33]
	v_mfma_f32_16x16x32_bf16 v[26:29], v[138:141], v[222:225], v[26:29]
	v_mfma_f32_16x16x32_bf16 v[14:17], v[122:125], v[230:233], v[14:17]
	v_mfma_f32_16x16x32_bf16 v[10:13], v[138:141], v[230:233], v[10:13]
	v_mfma_f32_16x16x32_bf16 v[62:65], v[134:137], v[190:193], v[62:65]
	v_mfma_f32_16x16x32_bf16 v[58:61], v[142:145], v[190:193], v[58:61]
	v_mfma_f32_16x16x32_bf16 v[46:49], v[134:137], v[218:221], v[46:49]
	v_mfma_f32_16x16x32_bf16 v[42:45], v[142:145], v[218:221], v[42:45]
	v_mfma_f32_16x16x32_bf16 v[30:33], v[134:137], v[226:229], v[30:33]
	v_mfma_f32_16x16x32_bf16 v[26:29], v[142:145], v[226:229], v[26:29]
	v_mfma_f32_16x16x32_bf16 v[14:17], v[134:137], v[234:237], v[14:17]
	v_mfma_f32_16x16x32_bf16 v[10:13], v[142:145], v[234:237], v[10:13]
	v_mfma_f32_16x16x32_bf16 v[54:57], v[146:149], v[186:189], v[54:57]
	v_mfma_f32_16x16x32_bf16 v[50:53], v[154:157], v[186:189], v[50:53]
	v_mfma_f32_16x16x32_bf16 v[38:41], v[146:149], v[194:197], v[38:41]
	v_mfma_f32_16x16x32_bf16 v[34:37], v[154:157], v[194:197], v[34:37]
	v_mfma_f32_16x16x32_bf16 v[22:25], v[146:149], v[222:225], v[22:25]
	v_mfma_f32_16x16x32_bf16 v[18:21], v[154:157], v[222:225], v[18:21]
	v_mfma_f32_16x16x32_bf16 v[6:9], v[146:149], v[230:233], v[6:9]
	v_mfma_f32_16x16x32_bf16 v[2:5], v[154:157], v[230:233], v[2:5]
	v_mfma_f32_16x16x32_bf16 v[54:57], v[150:153], v[190:193], v[54:57]
	v_mfma_f32_16x16x32_bf16 v[50:53], v[182:185], v[190:193], v[50:53]
	v_mfma_f32_16x16x32_bf16 v[38:41], v[150:153], v[218:221], v[38:41]
	v_mfma_f32_16x16x32_bf16 v[34:37], v[182:185], v[218:221], v[34:37]
	v_mfma_f32_16x16x32_bf16 v[22:25], v[150:153], v[226:229], v[22:25]
	v_mfma_f32_16x16x32_bf16 v[18:21], v[182:185], v[226:229], v[18:21]
	v_mfma_f32_16x16x32_bf16 v[6:9], v[150:153], v[234:237], v[6:9]
	v_mfma_f32_16x16x32_bf16 v[2:5], v[182:185], v[234:237], v[2:5]
	s_barrier
	s_add_i32 s54, 0, 0x18000
	s_add_i32 s55, 0, 0x1c000
	v_add_u32_e32 v142, s54, v199
	v_add_u32_e32 v182, s55, v199
	ds_read_b128 v[122:125], v142
	ds_read_b128 v[134:137], v142 offset:1024
	ds_read_b128 v[138:141], v142 offset:2048
	ds_read_b128 v[142:145], v142 offset:3072
	ds_read_b128 v[146:149], v182
	ds_read_b128 v[150:153], v182 offset:1024
	ds_read_b128 v[154:157], v182 offset:2048
	ds_read_b128 v[182:185], v182 offset:3072
	s_add_u32 s22, s28, 0x160000
	s_addc_u32 s23, s29, 0
	s_mov_b32 m0, s48
	v_lshl_add_u64 v[246:247], s[22:23], 0, v[162:163]
	ds_read_b128 v[186:189], v202 offset:32768
	ds_read_b128 v[190:193], v202 offset:33792
	ds_read_b128 v[194:197], v202 offset:34816
	ds_read_b128 v[218:221], v202 offset:35840
	ds_read_b128 v[222:225], v202 offset:36864
	ds_read_b128 v[226:229], v202 offset:37888
	ds_read_b128 v[230:233], v202 offset:38912
	ds_read_b128 v[234:237], v202 offset:39936
	global_load_lds_dwordx4 v[246:247], off
	v_lshl_add_u64 v[246:247], s[22:23], 0, v[160:161]
	s_mov_b32 m0, s49
	s_nop 0
	global_load_lds_dwordx4 v[246:247], off
	s_waitcnt vmcnt(8)
	s_waitcnt lgkmcnt(0)
	s_barrier
	v_mfma_f32_16x16x32_bf16 v[130:133], v[122:125], v[186:189], v[130:133]
	v_mfma_f32_16x16x32_bf16 v[126:129], v[138:141], v[186:189], v[126:129]
	v_mfma_f32_16x16x32_bf16 v[110:113], v[122:125], v[194:197], v[110:113]
	v_mfma_f32_16x16x32_bf16 v[106:109], v[138:141], v[194:197], v[106:109]
	v_mfma_f32_16x16x32_bf16 v[94:97], v[122:125], v[222:225], v[94:97]
	v_mfma_f32_16x16x32_bf16 v[90:93], v[138:141], v[222:225], v[90:93]
	v_mfma_f32_16x16x32_bf16 v[78:81], v[122:125], v[230:233], v[78:81]
	v_mfma_f32_16x16x32_bf16 v[74:77], v[138:141], v[230:233], v[74:77]
	v_mfma_f32_16x16x32_bf16 v[130:133], v[134:137], v[190:193], v[130:133]
	v_mfma_f32_16x16x32_bf16 v[126:129], v[142:145], v[190:193], v[126:129]
	v_mfma_f32_16x16x32_bf16 v[110:113], v[134:137], v[218:221], v[110:113]
	v_mfma_f32_16x16x32_bf16 v[106:109], v[142:145], v[218:221], v[106:109]
	v_mfma_f32_16x16x32_bf16 v[94:97], v[134:137], v[226:229], v[94:97]
	v_mfma_f32_16x16x32_bf16 v[90:93], v[142:145], v[226:229], v[90:93]
	v_mfma_f32_16x16x32_bf16 v[78:81], v[134:137], v[234:237], v[78:81]
	v_mfma_f32_16x16x32_bf16 v[74:77], v[142:145], v[234:237], v[74:77]
	v_mfma_f32_16x16x32_bf16 v[118:121], v[146:149], v[186:189], v[118:121]
	v_mfma_f32_16x16x32_bf16 v[114:117], v[154:157], v[186:189], v[114:117]
	v_mfma_f32_16x16x32_bf16 v[102:105], v[146:149], v[194:197], v[102:105]
	v_mfma_f32_16x16x32_bf16 v[98:101], v[154:157], v[194:197], v[98:101]
	v_mfma_f32_16x16x32_bf16 v[86:89], v[146:149], v[222:225], v[86:89]
	v_mfma_f32_16x16x32_bf16 v[82:85], v[154:157], v[222:225], v[82:85]
	v_mfma_f32_16x16x32_bf16 v[70:73], v[146:149], v[230:233], v[70:73]
	v_mfma_f32_16x16x32_bf16 v[66:69], v[154:157], v[230:233], v[66:69]
	v_mfma_f32_16x16x32_bf16 v[118:121], v[150:153], v[190:193], v[118:121]
	v_mfma_f32_16x16x32_bf16 v[114:117], v[182:185], v[190:193], v[114:117]
	v_mfma_f32_16x16x32_bf16 v[102:105], v[150:153], v[218:221], v[102:105]
	v_mfma_f32_16x16x32_bf16 v[98:101], v[182:185], v[218:221], v[98:101]
	v_mfma_f32_16x16x32_bf16 v[86:89], v[150:153], v[226:229], v[86:89]
	v_mfma_f32_16x16x32_bf16 v[82:85], v[182:185], v[226:229], v[82:85]
	v_mfma_f32_16x16x32_bf16 v[70:73], v[150:153], v[234:237], v[70:73]
	v_mfma_f32_16x16x32_bf16 v[66:69], v[182:185], v[234:237], v[66:69]
	s_barrier
; #define PG8_STAGE(bufoff, gbase, voff) do { _Pragma("unroll") for (int _i = 0; _i < 2; ++_i) \
;         __builtin_amdgcn_global_load_lds((const unsigned*)((const char*)(gbase) + (voff)[_i]), (PG8_LAS unsigned*)(lds + (bufoff) + ldsw + _i * 8192), 16, 0, 0); } while (0)
; #define PG8_LDA(dst, b, h) do { _Pragma("unroll") for (int m = 0; m < 4; ++m) _Pragma("unroll") for (int k = 0; k < 2; ++k) dst[m][k] = *(const PG8_LAS bf16x8*)(lds + PG8_SA(b, h) + aoff + m * 2048 + k * 1024); } while (0)
; #define PG8_MMA(ai, bj, At, Bt) do { __builtin_amdgcn_s_setprio(1); _Pragma("unroll") for (int m = 0; m < 4; ++m) _Pragma("unroll") for (int n = 0; n < 2; ++n) _Pragma("unroll") for (int k = 0; k < 2; ++k) \
;         acc[ai][bj][m][n] = __builtin_amdgcn_mfma_f32_16x16x32_bf16(Bt[n][k], At[m][k], acc[ai][bj][m][n], 0, 0, 0); __builtin_amdgcn_s_setprio(0); } while (0)
; #define PG8_WAIT_V(n) asm volatile("s_waitcnt vmcnt(" #n ")" ::: "memory")
; #define PG8_WAIT_L(n) asm volatile("s_waitcnt lgkmcnt(" #n ")" ::: "memory")
; #define PG8_BAR __builtin_amdgcn_s_barrier()
; #define PG8_SCHED __builtin_amdgcn_sched_barrier(0)
; template <class Epi, class Sched, bool ALIGN_EPI = false, bool SP2 = false>
; __device__ __forceinline__ void gemm_phase(PG8_LAS unsigned char* lds, const Gemm g, const Sched& S, const Epi& E) {
;     ...
;         for (int t = 0; t < nt; t += 2) {
;     ...
;             PG8_LDA(At, 1, 1); PG8_STAGE(PG8_SB(1, 0), b3, voffB); PG8_STAGE(PG8_SB(1, 1), b3 + hstep, voffB); PG8_STAGE(PG8_SA(1, 0), a3, voffA);
;             PG8_WAIT_V(8); PG8_WAIT_L(0); PG8_BAR; PG8_MMA(1, 0, At, B0); PG8_MMA(1, 1, At, B1); PG8_BAR; PG8_SCHED;
	s_add_i32 s22, s54, s2
	v_lshl_add_u64 v[238:239], v[238:239], 0, s[34:35]
	s_mov_b32 m0, s22
	ds_read_b128 v[186:189], v202 offset:49152
	ds_read_b128 v[190:193], v202 offset:50176
	ds_read_b128 v[194:197], v202 offset:51200
	ds_read_b128 v[218:221], v202 offset:52224
	ds_read_b128 v[222:225], v202 offset:53248
	ds_read_b128 v[226:229], v202 offset:54272
	ds_read_b128 v[230:233], v202 offset:55296
	ds_read_b128 v[234:237], v202 offset:56320
	global_load_lds_dwordx4 v[238:239], off
	s_add_i32 m0, s22, 0x2000
	s_add_u32 s22, s26, 0x160080
	v_lshl_add_u64 v[238:239], v[240:241], 0, s[34:35]
	s_addc_u32 s23, s27, 0
	s_add_i32 s26, s55, s2
	global_load_lds_dwordx4 v[238:239], off
	v_lshl_add_u64 v[238:239], s[22:23], 0, v[0:1]
	s_mov_b32 m0, s26
	s_nop 0
	global_load_lds_dwordx4 v[238:239], off
	v_lshl_add_u64 v[238:239], s[22:23], 0, v[158:159]
	s_add_i32 m0, s26, 0x2000
	s_nop 0
	global_load_lds_dwordx4 v[238:239], off
	v_lshl_add_u64 v[238:239], v[242:243], 0, s[34:35]
	s_mov_b32 m0, s51
	s_nop 0
	global_load_lds_dwordx4 v[238:239], off
	v_lshl_add_u64 v[238:239], v[244:245], 0, s[34:35]
	s_mov_b32 m0, s52
	s_nop 0
	global_load_lds_dwordx4 v[238:239], off
	s_waitcnt vmcnt(8)
	s_waitcnt lgkmcnt(0)
	s_barrier
	v_mfma_f32_16x16x32_bf16 v[62:65], v[122:125], v[186:189], v[62:65]
	v_mfma_f32_16x16x32_bf16 v[58:61], v[138:141], v[186:189], v[58:61]
	v_mfma_f32_16x16x32_bf16 v[46:49], v[122:125], v[194:197], v[46:49]
	v_mfma_f32_16x16x32_bf16 v[42:45], v[138:141], v[194:197], v[42:45]
	v_mfma_f32_16x16x32_bf16 v[30:33], v[122:125], v[222:225], v[30:33]
	v_mfma_f32_16x16x32_bf16 v[26:29], v[138:141], v[222:225], v[26:29]
	v_mfma_f32_16x16x32_bf16 v[14:17], v[122:125], v[230:233], v[14:17]
	v_mfma_f32_16x16x32_bf16 v[10:13], v[138:141], v[230:233], v[10:13]
	v_mfma_f32_16x16x32_bf16 v[62:65], v[134:137], v[190:193], v[62:65]
	v_mfma_f32_16x16x32_bf16 v[58:61], v[142:145], v[190:193], v[58:61]
	v_mfma_f32_16x16x32_bf16 v[46:49], v[134:137], v[218:221], v[46:49]
	v_mfma_f32_16x16x32_bf16 v[42:45], v[142:145], v[218:221], v[42:45]
	v_mfma_f32_16x16x32_bf16 v[30:33], v[134:137], v[226:229], v[30:33]
	v_mfma_f32_16x16x32_bf16 v[26:29], v[142:145], v[226:229], v[26:29]
	v_mfma_f32_16x16x32_bf16 v[14:17], v[134:137], v[234:237], v[14:17]
	v_mfma_f32_16x16x32_bf16 v[10:13], v[142:145], v[234:237], v[10:13]
	v_mfma_f32_16x16x32_bf16 v[54:57], v[146:149], v[186:189], v[54:57]
	v_mfma_f32_16x16x32_bf16 v[50:53], v[154:157], v[186:189], v[50:53]
	v_mfma_f32_16x16x32_bf16 v[38:41], v[146:149], v[194:197], v[38:41]
	v_mfma_f32_16x16x32_bf16 v[34:37], v[154:157], v[194:197], v[34:37]
	v_mfma_f32_16x16x32_bf16 v[22:25], v[146:149], v[222:225], v[22:25]
	v_mfma_f32_16x16x32_bf16 v[18:21], v[154:157], v[222:225], v[18:21]
	v_mfma_f32_16x16x32_bf16 v[6:9], v[146:149], v[230:233], v[6:9]
	v_mfma_f32_16x16x32_bf16 v[2:5], v[154:157], v[230:233], v[2:5]
	v_mfma_f32_16x16x32_bf16 v[54:57], v[150:153], v[190:193], v[54:57]
	v_mfma_f32_16x16x32_bf16 v[50:53], v[182:185], v[190:193], v[50:53]
	v_mfma_f32_16x16x32_bf16 v[38:41], v[150:153], v[218:221], v[38:41]
	v_mfma_f32_16x16x32_bf16 v[34:37], v[182:185], v[218:221], v[34:37]
	v_mfma_f32_16x16x32_bf16 v[22:25], v[150:153], v[226:229], v[22:25]
	v_mfma_f32_16x16x32_bf16 v[18:21], v[182:185], v[226:229], v[18:21]
	v_mfma_f32_16x16x32_bf16 v[6:9], v[150:153], v[234:237], v[6:9]
	v_mfma_f32_16x16x32_bf16 v[2:5], v[182:185], v[234:237], v[2:5]
	s_barrier
	s_add_i32 s78, s78, 2
	s_add_u32 s44, s44, 0x100
	s_addc_u32 s45, s45, 0
	s_cmpk_gt_u32 s78, 0x55
	s_mov_b64 s[22:23], s[24:25]
	s_cbranch_scc0 .LBB0_802
	s_and_b64 vcc, exec, s[6:7]
	s_cbranch_vccz .LBB0_805
	s_barrier
